# same progress-stepped s_setprio ladder (3-2-1-0 per barrier interval) added to the 40 k-tile segments of the fused gate/out-projection phase
# speedup vs baseline: 1.0047x; 1.0047x over previous
; #define LAS __attribute__((address_space(3)))
; #define P4_LD2(kt, R) do { R[0] = *(const u32x4*)(asrc + (kt) * 64); R[1] = *(const u32x4*)(asrc + (kt) * 64 + 32); R[2] = *(const u32x4*)(bsrc + (kt) * 64); R[3] = *(const u32x4*)(bsrc + (kt) * 64 + 32); \
;         R[4] = *(const u32x4*)(csrc + (kt) * 64); R[5] = *(const u32x4*)(csrc + (kt) * 64 + 32); } while (0)
; #define P4_ST2(boff, R) do { LAS char* nb_ = lds + (boff); *(LAS u32x4*)(nb_ + sdst) = R[0]; *(LAS u32x4*)(nb_ + sdst + 64) = R[1]; *(LAS u32x4*)(nb_ + P4_OPB + sdst) = R[2]; *(LAS u32x4*)(nb_ + P4_OPB + sdst + 64) = R[3]; \
;         *(LAS u32x4*)(nb_ + 2 * P4_OPB + sdst) = R[4]; *(LAS u32x4*)(nb_ + 2 * P4_OPB + sdst + 64) = R[5]; } while (0)
; __device__ __forceinline__ void p4_pass2(const bf16_t* __restrict__ A, int K, const bf16_t* __restrict__ B0, const bf16_t* __restrict__ B1, int rt, int ct, f32x16& a0, f32x16& a1, f32x16& m0, f32x16& m1, LAS char* lds, int tid, int r32, int hi, int wa, int wb) {
;     const bf16_t* asrc = A + (size_t)(rt * 128 + (tid >> 2)) * K + (tid & 3) * 8;
;     const bf16_t* bsrc = B0 + (size_t)(ct * 128 + (tid >> 2)) * K + (tid & 3) * 8;
;     const bf16_t* csrc = B1 + (size_t)(ct * 128 + (tid >> 2)) * K + (tid & 3) * 8;
;     const int sdst = (tid >> 2) * P4_PITCH + (tid & 3) * 16;
;     const int xoff = (wa * 32 + r32) * P4_PITCH + hi * 16, woff = P4_OPB + (wb * 64 + r32) * P4_PITCH + hi * 16;
;     const int nk = K >> 6;
;     u32x4 rA[6], rB[6];
;     ...
;     P4_LD2(0, rA); P4_ST2(0, rA); P4_LD2(1, rB);
;     __syncthreads();
;     a0 = (f32x16){}; a1 = (f32x16){}; m0 = (f32x16){}; m1 = (f32x16){};
;     ...
;     for (int kt = 0; kt < nk; kt += 2) { P4_STEP2(kt, rA, rB); P4_STEP2(kt + 1, rB, rA); }
;     ...
; }
; __device__ __forceinline__ void p4_unit(int rt, int ct, const bf16_t* H, const bf16_t* YA, const bf16_t* YM, const bf16_t* Wga, const bf16_t* Wgm, const bf16_t* Wa, const bf16_t* Wb, bf16_t* MERGED, LAS char* lds) {
;     int tid_ = threadIdx.x; asm volatile("" : "+v"(tid_)); const int tid = tid_, lane = tid & 63, r32 = lane & 31, hi = lane >> 5; const int wid = __builtin_amdgcn_readfirstlane(tid >> 6);
;     const int wa = wid & 3, wb = wid >> 2;
;     f32x16 g0, g1, m0, m1, c0, c1;
;     p4_pass2(H, 1024, Wga, Wgm, rt, ct, g0, g1, m0, m1, lds, tid, r32, hi, wa, wb);
.LBB0_848:
	v_mov_b32_e32 v0, v196
	s_and_b32 s65, s26, 0xffffff80
	s_and_b32 s23, s37, 0x380
	v_ashrrev_i32_e32 v4, 2, v0
	v_readfirstlane_b32 s3, v0
	v_add_u32_e32 v90, s65, v4
	v_and_b32_e32 v3, 31, v0
	v_bfe_u32 v165, v0, 5, 1
	v_lshlrev_b32_e32 v0, 4, v0
	v_add_u32_e32 v92, s23, v4
	s_lshr_b32 s22, s3, 1
	v_ashrrev_i32_e32 v91, 31, v90
	v_and_b32_e32 v0, 48, v0
	s_ashr_i32 s3, s3, 2
	v_ashrrev_i32_e32 v93, 31, v92
	s_and_b32 s33, s22, 0x60
	v_lshlrev_b64 v[100:101], 11, v[90:91]
	v_mad_u64_u32 v[104:105], s[38:39], v4, s92, v[0:1]
	s_and_b32 s22, s3, 0xffffffc0
	v_lshlrev_b64 v[98:99], 11, v[92:93]
	v_or_b32_e32 v166, s33, v3
	v_lshl_add_u64 v[4:5], s[6:7], 0, v[100:101]
	v_lshlrev_b32_e32 v2, 4, v165
	v_or_b32_e32 v3, s22, v3
	v_lshl_add_u64 v[6:7], s[14:15], 0, v[98:99]
	v_lshl_add_u64 v[8:9], s[16:17], 0, v[98:99]
	v_mul_u32_u24_e32 v10, 0x90, v166
	v_lshl_add_u64 v[102:103], v[4:5], 0, v[0:1]
	v_mad_u64_u32 v[106:107], s[38:39], v3, s92, v[2:3]
	v_lshl_add_u64 v[96:97], v[6:7], 0, v[0:1]
	v_lshl_add_u64 v[94:95], v[8:9], 0, v[0:1]
	v_add3_u32 v164, v10, v2, 0
	global_load_dwordx4 v[2:5], v[102:103], off
	global_load_dwordx4 v[6:9], v[102:103], off offset:64
	global_load_dwordx4 v[10:13], v[96:97], off
	global_load_dwordx4 v[14:17], v[96:97], off offset:64
	global_load_dwordx4 v[18:21], v[94:95], off
	global_load_dwordx4 v[22:25], v[94:95], off offset:64
	global_load_dwordx4 v[82:85], v[102:103], off offset:128
	global_load_dwordx4 v[86:89], v[102:103], off offset:192
	global_load_dwordx4 v[66:69], v[96:97], off offset:128
	global_load_dwordx4 v[70:73], v[96:97], off offset:192
	global_load_dwordx4 v[74:77], v[94:95], off offset:128
	global_load_dwordx4 v[78:81], v[94:95], off offset:192
	v_add_u32_e32 v162, 0, v104
	v_add_u32_e32 v163, 0, v106
	s_add_i32 s3, 0, 0x12000
	v_add_u32_e32 v107, 0x16800, v162
	v_lshl_add_u64 v[100:101], s[12:13], 0, v[100:101]
	v_lshl_add_u64 v[98:99], s[20:21], 0, v[98:99]
	v_lshl_add_u64 v[158:159], v[100:101], 0, v[0:1]
	v_lshl_add_u64 v[160:161], v[98:99], 0, v[0:1]
	s_lshl_b32 s42, s23, 1
	s_ashr_i32 s23, s22, 31
	s_add_i32 s25, s25, s24
	s_add_i32 s26, s26, s27
	s_add_i32 s37, s37, s64
	s_cmpk_lt_i32 s25, 0x400
	s_waitcnt vmcnt(0)
	ds_write_b128 v162, v[2:5]
	ds_write_b128 v162, v[6:9] offset:64
	ds_write_b128 v162, v[10:13] offset:18432
	ds_write_b128 v162, v[14:17] offset:18496
	ds_write_b128 v162, v[18:21] offset:36864
	ds_write_b128 v162, v[22:25] offset:36928
	s_waitcnt lgkmcnt(0)
	s_barrier
	s_setprio 3
	ds_read_b128 v[2:5], v163 offset:18432
	ds_read_b128 v[18:21], v164
	ds_read_b128 v[108:111], v164 offset:32
	ds_read_b128 v[112:115], v163 offset:18464
	s_waitcnt lgkmcnt(2)
	v_mfma_f32_32x32x16_bf16 v[50:65], v[2:5], v[18:21], 0
	ds_read_b128 v[2:5], v163 offset:23040
	ds_read_b128 v[116:119], v163 offset:23072
	ds_read_b128 v[22:25], v163 offset:36864
	ds_read_b128 v[120:123], v163 offset:36896
	s_waitcnt lgkmcnt(1)
	v_mfma_f32_32x32x16_bf16 v[34:49], v[22:25], v[18:21], 0
	ds_read_b128 v[22:25], v163 offset:41472
	ds_read_b128 v[124:127], v163 offset:41504
	v_mfma_f32_32x32x16_bf16 v[2:17], v[2:5], v[18:21], 0
	s_waitcnt lgkmcnt(1)
	v_mfma_f32_32x32x16_bf16 v[18:33], v[22:25], v[18:21], 0
	s_setprio 2
	v_mfma_f32_32x32x16_bf16 v[50:65], v[112:115], v[108:111], v[50:65]
	v_mfma_f32_32x32x16_bf16 v[2:17], v[116:119], v[108:111], v[2:17]
	v_mfma_f32_32x32x16_bf16 v[34:49], v[120:123], v[108:111], v[34:49]
	s_waitcnt lgkmcnt(0)
	v_mfma_f32_32x32x16_bf16 v[18:33], v[124:127], v[108:111], v[18:33]
	ds_read_b128 v[108:111], v163 offset:18496
	ds_read_b128 v[112:115], v164 offset:64
	ds_read_b128 v[116:119], v164 offset:96
	ds_read_b128 v[120:123], v163 offset:18528
	s_waitcnt lgkmcnt(2)
	v_mfma_f32_32x32x16_bf16 v[50:65], v[108:111], v[112:115], v[50:65]
	ds_read_b128 v[108:111], v163 offset:23104
	ds_read_b128 v[124:127], v163 offset:23136
	s_waitcnt lgkmcnt(1)
	s_setprio 1
	v_mfma_f32_32x32x16_bf16 v[2:17], v[108:111], v[112:115], v[2:17]
	ds_read_b128 v[108:111], v163 offset:36928
	ds_read_b128 v[128:131], v163 offset:36960
	s_waitcnt lgkmcnt(1)
	v_mfma_f32_32x32x16_bf16 v[34:49], v[108:111], v[112:115], v[34:49]
	ds_read_b128 v[108:111], v163 offset:41536
	ds_read_b128 v[132:135], v163 offset:41568
	v_mfma_f32_32x32x16_bf16 v[50:65], v[120:123], v[116:119], v[50:65]
	s_waitcnt lgkmcnt(1)
	v_mfma_f32_32x32x16_bf16 v[18:33], v[108:111], v[112:115], v[18:33]
	v_add_u32_e32 v108, s3, v104
	v_add_u32_e32 v104, 0x4800, v106
	v_add_u32_e32 v105, 0, v104
	global_load_dwordx4 v[110:113], v[102:103], off offset:256
	v_add_u32_e32 v104, s3, v104
	v_mfma_f32_32x32x16_bf16 v[2:17], v[124:127], v[116:119], v[2:17]
	s_setprio 0
	global_load_dwordx4 v[120:123], v[102:103], off offset:320
	global_load_dwordx4 v[124:127], v[96:97], off offset:256
	global_load_dwordx4 v[136:139], v[96:97], off offset:320
	global_load_dwordx4 v[140:143], v[94:95], off offset:256
	global_load_dwordx4 v[144:147], v[94:95], off offset:320
	ds_write_b128 v162, v[82:85] offset:55296
	ds_write_b128 v162, v[86:89] offset:55360
	ds_write_b128 v108, v[66:69]
	ds_write_b128 v108, v[70:73] offset:64
	ds_write_b128 v107, v[74:77]
	ds_write_b128 v107, v[78:81] offset:64
	s_waitcnt lgkmcnt(0)
	s_barrier
; __device__ __forceinline__ void p4_pass2(const bf16_t* __restrict__ A, int K, const bf16_t* __restrict__ B0, const bf16_t* __restrict__ B1, int rt, int ct, f32x16& a0, f32x16& a1, f32x16& m0, f32x16& m1, LAS char* lds, int tid, int r32, int hi, int wa, int wb) {
;     ...
;     for (int kt = 0; kt < nk; kt += 2) { P4_STEP2(kt, rA, rB); P4_STEP2(kt + 1, rB, rA); }
	s_setprio 3
	ds_read_b128 v[66:69], v105 offset:55296
	ds_read_b128 v[70:73], v164 offset:55296
	ds_read_b128 v[74:77], v164 offset:55328
	ds_read_b128 v[78:81], v105 offset:55328
	v_mfma_f32_32x32x16_bf16 v[34:49], v[128:131], v[116:119], v[34:49]
	s_waitcnt lgkmcnt(2)
	v_mfma_f32_32x32x16_bf16 v[50:65], v[66:69], v[70:73], v[50:65]
	ds_read_b128 v[66:69], v105 offset:59904
	ds_read_b128 v[82:85], v105 offset:59936
	v_mfma_f32_32x32x16_bf16 v[18:33], v[132:135], v[116:119], v[18:33]
	s_waitcnt lgkmcnt(1)
	v_mfma_f32_32x32x16_bf16 v[2:17], v[66:69], v[70:73], v[2:17]
	ds_read_b128 v[66:69], v104
	ds_read_b128 v[86:89], v104 offset:32
	s_waitcnt lgkmcnt(1)
	v_mfma_f32_32x32x16_bf16 v[34:49], v[66:69], v[70:73], v[34:49]
	ds_read_b128 v[66:69], v104 offset:4608
	ds_read_b128 v[114:117], v104 offset:4640
	s_waitcnt lgkmcnt(1)
	s_setprio 2
	v_mfma_f32_32x32x16_bf16 v[18:33], v[66:69], v[70:73], v[18:33]
	v_mfma_f32_32x32x16_bf16 v[50:65], v[78:81], v[74:77], v[50:65]
	v_mfma_f32_32x32x16_bf16 v[2:17], v[82:85], v[74:77], v[2:17]
	v_mfma_f32_32x32x16_bf16 v[34:49], v[86:89], v[74:77], v[34:49]
	s_waitcnt lgkmcnt(0)
	v_mfma_f32_32x32x16_bf16 v[18:33], v[114:117], v[74:77], v[18:33]
	ds_read_b128 v[66:69], v105 offset:55360
	ds_read_b128 v[70:73], v164 offset:55360
	ds_read_b128 v[74:77], v164 offset:55392
	ds_read_b128 v[78:81], v105 offset:55392
	s_waitcnt lgkmcnt(2)
	v_mfma_f32_32x32x16_bf16 v[50:65], v[66:69], v[70:73], v[50:65]
	ds_read_b128 v[66:69], v105 offset:59968
	ds_read_b128 v[82:85], v105 offset:60000
	s_waitcnt lgkmcnt(1)
	s_setprio 1
	v_mfma_f32_32x32x16_bf16 v[2:17], v[66:69], v[70:73], v[2:17]
	ds_read_b128 v[66:69], v104 offset:64
	ds_read_b128 v[86:89], v104 offset:96
	s_waitcnt lgkmcnt(1)
	v_mfma_f32_32x32x16_bf16 v[34:49], v[66:69], v[70:73], v[34:49]
	ds_read_b128 v[66:69], v104 offset:4672
	ds_read_b128 v[114:117], v104 offset:4704
	s_waitcnt lgkmcnt(1)
	v_mfma_f32_32x32x16_bf16 v[18:33], v[66:69], v[70:73], v[18:33]
	v_mfma_f32_32x32x16_bf16 v[50:65], v[78:81], v[74:77], v[50:65]
	v_mfma_f32_32x32x16_bf16 v[2:17], v[82:85], v[74:77], v[2:17]
	v_mfma_f32_32x32x16_bf16 v[34:49], v[86:89], v[74:77], v[34:49]
	s_setprio 0
	global_load_dwordx4 v[66:69], v[102:103], off offset:384
	global_load_dwordx4 v[70:73], v[102:103], off offset:448
	global_load_dwordx4 v[78:81], v[96:97], off offset:384
	global_load_dwordx4 v[82:85], v[96:97], off offset:448
	global_load_dwordx4 v[86:89], v[94:95], off offset:384
	global_load_dwordx4 v[128:131], v[94:95], off offset:448
	s_waitcnt vmcnt(11)
	ds_write_b128 v162, v[110:113]
	s_waitcnt vmcnt(10)
	ds_write_b128 v162, v[120:123] offset:64
	s_waitcnt vmcnt(9)
	ds_write_b128 v162, v[124:127] offset:18432
	s_waitcnt vmcnt(8)
	ds_write_b128 v162, v[136:139] offset:18496
	s_waitcnt vmcnt(7)
	ds_write_b128 v162, v[140:143] offset:36864
	s_waitcnt vmcnt(6)
	ds_write_b128 v162, v[144:147] offset:36928
	s_waitcnt lgkmcnt(0)
	s_barrier
	s_setprio 3
	v_mfma_f32_32x32x16_bf16 v[18:33], v[114:117], v[74:77], v[18:33]
	ds_read_b128 v[74:77], v163 offset:18432
	ds_read_b128 v[110:113], v164
	ds_read_b128 v[114:117], v164 offset:32
	ds_read_b128 v[118:121], v163 offset:18464
	s_waitcnt lgkmcnt(2)
	v_mfma_f32_32x32x16_bf16 v[50:65], v[74:77], v[110:113], v[50:65]
	ds_read_b128 v[74:77], v163 offset:23040
	ds_read_b128 v[122:125], v163 offset:23072
	s_waitcnt lgkmcnt(1)
	v_mfma_f32_32x32x16_bf16 v[2:17], v[74:77], v[110:113], v[2:17]
	ds_read_b128 v[74:77], v163 offset:36864
	ds_read_b128 v[132:135], v163 offset:36896
	s_waitcnt lgkmcnt(1)
	v_mfma_f32_32x32x16_bf16 v[34:49], v[74:77], v[110:113], v[34:49]
	ds_read_b128 v[74:77], v163 offset:41472
	ds_read_b128 v[136:139], v163 offset:41504
	s_waitcnt lgkmcnt(1)
	v_mfma_f32_32x32x16_bf16 v[18:33], v[74:77], v[110:113], v[18:33]
	s_setprio 2
	v_mfma_f32_32x32x16_bf16 v[50:65], v[118:121], v[114:117], v[50:65]
	v_mfma_f32_32x32x16_bf16 v[2:17], v[122:125], v[114:117], v[2:17]
	v_mfma_f32_32x32x16_bf16 v[34:49], v[132:135], v[114:117], v[34:49]
	s_waitcnt lgkmcnt(0)
	v_mfma_f32_32x32x16_bf16 v[18:33], v[136:139], v[114:117], v[18:33]
	ds_read_b128 v[74:77], v163 offset:18496
	ds_read_b128 v[110:113], v164 offset:64
	ds_read_b128 v[114:117], v164 offset:96
	ds_read_b128 v[118:121], v163 offset:18528
	s_waitcnt lgkmcnt(2)
	v_mfma_f32_32x32x16_bf16 v[50:65], v[74:77], v[110:113], v[50:65]
	ds_read_b128 v[74:77], v163 offset:23104
	ds_read_b128 v[122:125], v163 offset:23136
	s_waitcnt lgkmcnt(1)
	s_setprio 1
	v_mfma_f32_32x32x16_bf16 v[2:17], v[74:77], v[110:113], v[2:17]
	ds_read_b128 v[74:77], v163 offset:36928
	ds_read_b128 v[132:135], v163 offset:36960
	s_waitcnt lgkmcnt(1)
	v_mfma_f32_32x32x16_bf16 v[34:49], v[74:77], v[110:113], v[34:49]
	ds_read_b128 v[74:77], v163 offset:41536
	ds_read_b128 v[136:139], v163 offset:41568
	v_mfma_f32_32x32x16_bf16 v[50:65], v[118:121], v[114:117], v[50:65]
	s_waitcnt lgkmcnt(1)
	v_mfma_f32_32x32x16_bf16 v[18:33], v[74:77], v[110:113], v[18:33]
	global_load_dwordx4 v[74:77], v[102:103], off offset:512
	v_mfma_f32_32x32x16_bf16 v[2:17], v[122:125], v[114:117], v[2:17]
	s_setprio 0
	global_load_dwordx4 v[110:113], v[102:103], off offset:576
	global_load_dwordx4 v[118:121], v[96:97], off offset:512
	global_load_dwordx4 v[122:125], v[96:97], off offset:576
	global_load_dwordx4 v[140:143], v[94:95], off offset:512
	global_load_dwordx4 v[144:147], v[94:95], off offset:576
	s_waitcnt vmcnt(11)
	ds_write_b128 v162, v[66:69] offset:55296
	s_waitcnt vmcnt(10)
	ds_write_b128 v162, v[70:73] offset:55360
	s_waitcnt vmcnt(9)
	ds_write_b128 v108, v[78:81]
	s_waitcnt vmcnt(8)
	ds_write_b128 v108, v[82:85] offset:64
	s_waitcnt vmcnt(7)
	ds_write_b128 v107, v[86:89]
	s_waitcnt vmcnt(6)
	ds_write_b128 v107, v[128:131] offset:64
	s_waitcnt lgkmcnt(0)
	s_barrier
; __device__ __forceinline__ void p4_pass2(const bf16_t* __restrict__ A, int K, const bf16_t* __restrict__ B0, const bf16_t* __restrict__ B1, int rt, int ct, f32x16& a0, f32x16& a1, f32x16& m0, f32x16& m1, LAS char* lds, int tid, int r32, int hi, int wa, int wb) {
;     ...
;     for (int kt = 0; kt < nk; kt += 2) { P4_STEP2(kt, rA, rB); P4_STEP2(kt + 1, rB, rA); }
	s_setprio 3
	ds_read_b128 v[66:69], v105 offset:55296
	ds_read_b128 v[70:73], v164 offset:55296
	ds_read_b128 v[78:81], v164 offset:55328
	ds_read_b128 v[82:85], v105 offset:55328
	v_mfma_f32_32x32x16_bf16 v[34:49], v[132:135], v[114:117], v[34:49]
	s_waitcnt lgkmcnt(2)
	v_mfma_f32_32x32x16_bf16 v[50:65], v[66:69], v[70:73], v[50:65]
	ds_read_b128 v[66:69], v105 offset:59904
	ds_read_b128 v[86:89], v105 offset:59936
	v_mfma_f32_32x32x16_bf16 v[18:33], v[136:139], v[114:117], v[18:33]
	s_waitcnt lgkmcnt(1)
	v_mfma_f32_32x32x16_bf16 v[2:17], v[66:69], v[70:73], v[2:17]
	ds_read_b128 v[66:69], v104
	ds_read_b128 v[114:117], v104 offset:32
	s_waitcnt lgkmcnt(1)
	v_mfma_f32_32x32x16_bf16 v[34:49], v[66:69], v[70:73], v[34:49]
	ds_read_b128 v[66:69], v104 offset:4608
	ds_read_b128 v[126:129], v104 offset:4640
	s_waitcnt lgkmcnt(1)
	s_setprio 2
	v_mfma_f32_32x32x16_bf16 v[18:33], v[66:69], v[70:73], v[18:33]
	v_mfma_f32_32x32x16_bf16 v[50:65], v[82:85], v[78:81], v[50:65]
	v_mfma_f32_32x32x16_bf16 v[2:17], v[86:89], v[78:81], v[2:17]
	v_mfma_f32_32x32x16_bf16 v[34:49], v[114:117], v[78:81], v[34:49]
	s_waitcnt lgkmcnt(0)
	v_mfma_f32_32x32x16_bf16 v[18:33], v[126:129], v[78:81], v[18:33]
	ds_read_b128 v[66:69], v105 offset:55360
	ds_read_b128 v[70:73], v164 offset:55360
	ds_read_b128 v[78:81], v164 offset:55392
	ds_read_b128 v[82:85], v105 offset:55392
	s_waitcnt lgkmcnt(2)
	v_mfma_f32_32x32x16_bf16 v[50:65], v[66:69], v[70:73], v[50:65]
	ds_read_b128 v[66:69], v105 offset:59968
	ds_read_b128 v[86:89], v105 offset:60000
	s_waitcnt lgkmcnt(1)
	s_setprio 1
	v_mfma_f32_32x32x16_bf16 v[2:17], v[66:69], v[70:73], v[2:17]
	ds_read_b128 v[66:69], v104 offset:64
	ds_read_b128 v[114:117], v104 offset:96
	s_waitcnt lgkmcnt(1)
	v_mfma_f32_32x32x16_bf16 v[34:49], v[66:69], v[70:73], v[34:49]
	ds_read_b128 v[66:69], v104 offset:4672
	ds_read_b128 v[126:129], v104 offset:4704
	s_waitcnt lgkmcnt(1)
	v_mfma_f32_32x32x16_bf16 v[18:33], v[66:69], v[70:73], v[18:33]
	v_mfma_f32_32x32x16_bf16 v[50:65], v[82:85], v[78:81], v[50:65]
	v_mfma_f32_32x32x16_bf16 v[2:17], v[86:89], v[78:81], v[2:17]
	v_mfma_f32_32x32x16_bf16 v[34:49], v[114:117], v[78:81], v[34:49]
	s_setprio 0
	global_load_dwordx4 v[66:69], v[102:103], off offset:640
	global_load_dwordx4 v[70:73], v[102:103], off offset:704
	global_load_dwordx4 v[82:85], v[96:97], off offset:640
	global_load_dwordx4 v[86:89], v[96:97], off offset:704
	global_load_dwordx4 v[114:117], v[94:95], off offset:640
	global_load_dwordx4 v[130:133], v[94:95], off offset:704
	s_waitcnt vmcnt(11)
	ds_write_b128 v162, v[74:77]
	s_waitcnt vmcnt(10)
	ds_write_b128 v162, v[110:113] offset:64
	s_waitcnt vmcnt(9)
	ds_write_b128 v162, v[118:121] offset:18432
	s_waitcnt vmcnt(8)
	ds_write_b128 v162, v[122:125] offset:18496
	s_waitcnt vmcnt(7)
	ds_write_b128 v162, v[140:143] offset:36864
	s_waitcnt vmcnt(6)
	ds_write_b128 v162, v[144:147] offset:36928
	s_waitcnt lgkmcnt(0)
	s_barrier
	s_setprio 3
	v_mfma_f32_32x32x16_bf16 v[18:33], v[126:129], v[78:81], v[18:33]
	ds_read_b128 v[74:77], v163 offset:18432
	ds_read_b128 v[78:81], v164
	ds_read_b128 v[110:113], v164 offset:32
	ds_read_b128 v[118:121], v163 offset:18464
	s_waitcnt lgkmcnt(2)
	v_mfma_f32_32x32x16_bf16 v[50:65], v[74:77], v[78:81], v[50:65]
	ds_read_b128 v[74:77], v163 offset:23040
	ds_read_b128 v[122:125], v163 offset:23072
	s_waitcnt lgkmcnt(1)
	v_mfma_f32_32x32x16_bf16 v[2:17], v[74:77], v[78:81], v[2:17]
	ds_read_b128 v[74:77], v163 offset:36864
	ds_read_b128 v[126:129], v163 offset:36896
	s_waitcnt lgkmcnt(1)
	v_mfma_f32_32x32x16_bf16 v[34:49], v[74:77], v[78:81], v[34:49]
	ds_read_b128 v[74:77], v163 offset:41472
	ds_read_b128 v[134:137], v163 offset:41504
	s_waitcnt lgkmcnt(1)
	v_mfma_f32_32x32x16_bf16 v[18:33], v[74:77], v[78:81], v[18:33]
	s_setprio 2
	v_mfma_f32_32x32x16_bf16 v[50:65], v[118:121], v[110:113], v[50:65]
	v_mfma_f32_32x32x16_bf16 v[2:17], v[122:125], v[110:113], v[2:17]
	v_mfma_f32_32x32x16_bf16 v[34:49], v[126:129], v[110:113], v[34:49]
	s_waitcnt lgkmcnt(0)
	v_mfma_f32_32x32x16_bf16 v[18:33], v[134:137], v[110:113], v[18:33]
	ds_read_b128 v[74:77], v163 offset:18496
	ds_read_b128 v[78:81], v164 offset:64
	ds_read_b128 v[110:113], v164 offset:96
	ds_read_b128 v[118:121], v163 offset:18528
	s_waitcnt lgkmcnt(2)
	v_mfma_f32_32x32x16_bf16 v[50:65], v[74:77], v[78:81], v[50:65]
	ds_read_b128 v[74:77], v163 offset:23104
	ds_read_b128 v[122:125], v163 offset:23136
	s_waitcnt lgkmcnt(1)
	s_setprio 1
	v_mfma_f32_32x32x16_bf16 v[2:17], v[74:77], v[78:81], v[2:17]
	ds_read_b128 v[74:77], v163 offset:36928
	ds_read_b128 v[126:129], v163 offset:36960
	s_waitcnt lgkmcnt(1)
	v_mfma_f32_32x32x16_bf16 v[34:49], v[74:77], v[78:81], v[34:49]
	ds_read_b128 v[74:77], v163 offset:41536
	ds_read_b128 v[134:137], v163 offset:41568
	s_waitcnt lgkmcnt(1)
	v_mfma_f32_32x32x16_bf16 v[18:33], v[74:77], v[78:81], v[18:33]
	global_load_dwordx4 v[74:77], v[102:103], off offset:768
	v_mfma_f32_32x32x16_bf16 v[50:65], v[118:121], v[110:113], v[50:65]
	v_mfma_f32_32x32x16_bf16 v[2:17], v[122:125], v[110:113], v[2:17]
	s_setprio 0
	global_load_dwordx4 v[78:81], v[102:103], off offset:832
	global_load_dwordx4 v[118:121], v[96:97], off offset:768
	global_load_dwordx4 v[122:125], v[96:97], off offset:832
	global_load_dwordx4 v[138:141], v[94:95], off offset:768
	global_load_dwordx4 v[142:145], v[94:95], off offset:832
	s_waitcnt vmcnt(11)
	ds_write_b128 v162, v[66:69] offset:55296
	s_waitcnt vmcnt(10)
	ds_write_b128 v162, v[70:73] offset:55360
	s_waitcnt vmcnt(9)
	ds_write_b128 v108, v[82:85]
	s_waitcnt vmcnt(8)
	ds_write_b128 v108, v[86:89] offset:64
	s_waitcnt vmcnt(7)
	ds_write_b128 v107, v[114:117]
	s_waitcnt vmcnt(6)
	ds_write_b128 v107, v[130:133] offset:64
	s_waitcnt lgkmcnt(0)
	s_barrier
; __device__ __forceinline__ void p4_pass2(const bf16_t* __restrict__ A, int K, const bf16_t* __restrict__ B0, const bf16_t* __restrict__ B1, int rt, int ct, f32x16& a0, f32x16& a1, f32x16& m0, f32x16& m1, LAS char* lds, int tid, int r32, int hi, int wa, int wb) {
;     ...
;     for (int kt = 0; kt < nk; kt += 2) { P4_STEP2(kt, rA, rB); P4_STEP2(kt + 1, rB, rA); }
	s_setprio 3
	ds_read_b128 v[66:69], v105 offset:55296
	ds_read_b128 v[70:73], v164 offset:55296
	ds_read_b128 v[82:85], v164 offset:55328
	ds_read_b128 v[86:89], v105 offset:55328
	v_mfma_f32_32x32x16_bf16 v[34:49], v[126:129], v[110:113], v[34:49]
	v_mfma_f32_32x32x16_bf16 v[18:33], v[134:137], v[110:113], v[18:33]
	s_waitcnt lgkmcnt(2)
	v_mfma_f32_32x32x16_bf16 v[50:65], v[66:69], v[70:73], v[50:65]
	ds_read_b128 v[66:69], v105 offset:59904
	ds_read_b128 v[110:113], v105 offset:59936
	s_waitcnt lgkmcnt(1)
	v_mfma_f32_32x32x16_bf16 v[2:17], v[66:69], v[70:73], v[2:17]
	ds_read_b128 v[66:69], v104
	ds_read_b128 v[114:117], v104 offset:32
	s_waitcnt lgkmcnt(1)
	v_mfma_f32_32x32x16_bf16 v[34:49], v[66:69], v[70:73], v[34:49]
	ds_read_b128 v[66:69], v104 offset:4608
	ds_read_b128 v[126:129], v104 offset:4640
	s_waitcnt lgkmcnt(1)
	s_setprio 2
	v_mfma_f32_32x32x16_bf16 v[18:33], v[66:69], v[70:73], v[18:33]
	v_mfma_f32_32x32x16_bf16 v[50:65], v[86:89], v[82:85], v[50:65]
	v_mfma_f32_32x32x16_bf16 v[2:17], v[110:113], v[82:85], v[2:17]
	v_mfma_f32_32x32x16_bf16 v[34:49], v[114:117], v[82:85], v[34:49]
	s_waitcnt lgkmcnt(0)
	v_mfma_f32_32x32x16_bf16 v[18:33], v[126:129], v[82:85], v[18:33]
	ds_read_b128 v[66:69], v105 offset:55360
	ds_read_b128 v[70:73], v164 offset:55360
	ds_read_b128 v[82:85], v164 offset:55392
	ds_read_b128 v[86:89], v105 offset:55392
	s_waitcnt lgkmcnt(2)
	v_mfma_f32_32x32x16_bf16 v[50:65], v[66:69], v[70:73], v[50:65]
	ds_read_b128 v[66:69], v105 offset:59968
	ds_read_b128 v[110:113], v105 offset:60000
	s_waitcnt lgkmcnt(1)
	s_setprio 1
	v_mfma_f32_32x32x16_bf16 v[2:17], v[66:69], v[70:73], v[2:17]
	ds_read_b128 v[66:69], v104 offset:64
	ds_read_b128 v[114:117], v104 offset:96
	s_waitcnt lgkmcnt(1)
	v_mfma_f32_32x32x16_bf16 v[34:49], v[66:69], v[70:73], v[34:49]
	ds_read_b128 v[66:69], v104 offset:4672
	ds_read_b128 v[126:129], v104 offset:4704
	s_waitcnt lgkmcnt(1)
	v_mfma_f32_32x32x16_bf16 v[18:33], v[66:69], v[70:73], v[18:33]
	v_mfma_f32_32x32x16_bf16 v[50:65], v[86:89], v[82:85], v[50:65]
	v_mfma_f32_32x32x16_bf16 v[2:17], v[110:113], v[82:85], v[2:17]
	v_mfma_f32_32x32x16_bf16 v[34:49], v[114:117], v[82:85], v[34:49]
	s_setprio 0
	global_load_dwordx4 v[66:69], v[102:103], off offset:896
	global_load_dwordx4 v[70:73], v[102:103], off offset:960
	global_load_dwordx4 v[86:89], v[96:97], off offset:896
	global_load_dwordx4 v[110:113], v[96:97], off offset:960
	global_load_dwordx4 v[114:117], v[94:95], off offset:896
	global_load_dwordx4 v[130:133], v[94:95], off offset:960
	s_waitcnt vmcnt(11)
	ds_write_b128 v162, v[74:77]
	s_waitcnt vmcnt(10)
	ds_write_b128 v162, v[78:81] offset:64
	s_waitcnt vmcnt(9)
	ds_write_b128 v162, v[118:121] offset:18432
	s_waitcnt vmcnt(8)
	ds_write_b128 v162, v[122:125] offset:18496
	s_waitcnt vmcnt(7)
	ds_write_b128 v162, v[138:141] offset:36864
	s_waitcnt vmcnt(6)
	ds_write_b128 v162, v[142:145] offset:36928
	s_waitcnt lgkmcnt(0)
	s_barrier
	s_setprio 3
	v_mfma_f32_32x32x16_bf16 v[18:33], v[126:129], v[82:85], v[18:33]
	ds_read_b128 v[74:77], v163 offset:18432
	ds_read_b128 v[78:81], v164
	ds_read_b128 v[82:85], v164 offset:32
	ds_read_b128 v[118:121], v163 offset:18464
	s_waitcnt lgkmcnt(2)
	v_mfma_f32_32x32x16_bf16 v[50:65], v[74:77], v[78:81], v[50:65]
	ds_read_b128 v[74:77], v163 offset:23040
	ds_read_b128 v[122:125], v163 offset:23072
	s_waitcnt lgkmcnt(1)
	v_mfma_f32_32x32x16_bf16 v[2:17], v[74:77], v[78:81], v[2:17]
	ds_read_b128 v[74:77], v163 offset:36864
	ds_read_b128 v[126:129], v163 offset:36896
	s_waitcnt lgkmcnt(1)
	v_mfma_f32_32x32x16_bf16 v[34:49], v[74:77], v[78:81], v[34:49]
	ds_read_b128 v[74:77], v163 offset:41472
	ds_read_b128 v[134:137], v163 offset:41504
	s_waitcnt lgkmcnt(1)
	v_mfma_f32_32x32x16_bf16 v[18:33], v[74:77], v[78:81], v[18:33]
	s_setprio 2
	v_mfma_f32_32x32x16_bf16 v[50:65], v[118:121], v[82:85], v[50:65]
	v_mfma_f32_32x32x16_bf16 v[2:17], v[122:125], v[82:85], v[2:17]
	v_mfma_f32_32x32x16_bf16 v[34:49], v[126:129], v[82:85], v[34:49]
	s_waitcnt lgkmcnt(0)
	v_mfma_f32_32x32x16_bf16 v[18:33], v[134:137], v[82:85], v[18:33]
	ds_read_b128 v[74:77], v163 offset:18496
	ds_read_b128 v[78:81], v164 offset:64
	ds_read_b128 v[82:85], v164 offset:96
	ds_read_b128 v[118:121], v163 offset:18528
	s_waitcnt lgkmcnt(2)
	v_mfma_f32_32x32x16_bf16 v[50:65], v[74:77], v[78:81], v[50:65]
	ds_read_b128 v[74:77], v163 offset:23104
	ds_read_b128 v[122:125], v163 offset:23136
	s_waitcnt lgkmcnt(1)
	s_setprio 1
	v_mfma_f32_32x32x16_bf16 v[2:17], v[74:77], v[78:81], v[2:17]
	ds_read_b128 v[74:77], v163 offset:36928
	ds_read_b128 v[126:129], v163 offset:36960
	s_waitcnt lgkmcnt(1)
	v_mfma_f32_32x32x16_bf16 v[34:49], v[74:77], v[78:81], v[34:49]
	ds_read_b128 v[74:77], v163 offset:41536
	ds_read_b128 v[134:137], v163 offset:41568
	s_waitcnt lgkmcnt(1)
	v_mfma_f32_32x32x16_bf16 v[18:33], v[74:77], v[78:81], v[18:33]
	global_load_dwordx4 v[74:77], v[102:103], off offset:1024
	v_mfma_f32_32x32x16_bf16 v[50:65], v[118:121], v[82:85], v[50:65]
	v_mfma_f32_32x32x16_bf16 v[2:17], v[122:125], v[82:85], v[2:17]
	s_setprio 0
	global_load_dwordx4 v[78:81], v[102:103], off offset:1088
	global_load_dwordx4 v[118:121], v[96:97], off offset:1024
	global_load_dwordx4 v[122:125], v[96:97], off offset:1088
	global_load_dwordx4 v[138:141], v[94:95], off offset:1024
	global_load_dwordx4 v[142:145], v[94:95], off offset:1088
	s_waitcnt vmcnt(11)
	ds_write_b128 v162, v[66:69] offset:55296
	s_waitcnt vmcnt(10)
	ds_write_b128 v162, v[70:73] offset:55360
	s_waitcnt vmcnt(9)
	ds_write_b128 v108, v[86:89]
	s_waitcnt vmcnt(8)
	ds_write_b128 v108, v[110:113] offset:64
	s_waitcnt vmcnt(7)
	ds_write_b128 v107, v[114:117]
	s_waitcnt vmcnt(6)
	ds_write_b128 v107, v[130:133] offset:64
	s_waitcnt lgkmcnt(0)
	s_barrier
; __device__ __forceinline__ void p4_pass2(const bf16_t* __restrict__ A, int K, const bf16_t* __restrict__ B0, const bf16_t* __restrict__ B1, int rt, int ct, f32x16& a0, f32x16& a1, f32x16& m0, f32x16& m1, LAS char* lds, int tid, int r32, int hi, int wa, int wb) {
;     ...
;     for (int kt = 0; kt < nk; kt += 2) { P4_STEP2(kt, rA, rB); P4_STEP2(kt + 1, rB, rA); }
	s_setprio 3
	v_mfma_f32_32x32x16_bf16 v[34:49], v[126:129], v[82:85], v[34:49]
	v_mfma_f32_32x32x16_bf16 v[18:33], v[134:137], v[82:85], v[18:33]
	ds_read_b128 v[66:69], v105 offset:55296
	ds_read_b128 v[70:73], v164 offset:55296
	ds_read_b128 v[82:85], v164 offset:55328
	ds_read_b128 v[86:89], v105 offset:55328
	s_waitcnt lgkmcnt(2)
	v_mfma_f32_32x32x16_bf16 v[50:65], v[66:69], v[70:73], v[50:65]
	ds_read_b128 v[66:69], v105 offset:59904
	ds_read_b128 v[110:113], v105 offset:59936
	s_waitcnt lgkmcnt(1)
	v_mfma_f32_32x32x16_bf16 v[2:17], v[66:69], v[70:73], v[2:17]
	ds_read_b128 v[66:69], v104
	ds_read_b128 v[114:117], v104 offset:32
	s_waitcnt lgkmcnt(1)
	v_mfma_f32_32x32x16_bf16 v[34:49], v[66:69], v[70:73], v[34:49]
	ds_read_b128 v[66:69], v104 offset:4608
	ds_read_b128 v[126:129], v104 offset:4640
	s_waitcnt lgkmcnt(1)
	s_setprio 2
	v_mfma_f32_32x32x16_bf16 v[18:33], v[66:69], v[70:73], v[18:33]
	v_mfma_f32_32x32x16_bf16 v[50:65], v[86:89], v[82:85], v[50:65]
	v_mfma_f32_32x32x16_bf16 v[2:17], v[110:113], v[82:85], v[2:17]
	v_mfma_f32_32x32x16_bf16 v[34:49], v[114:117], v[82:85], v[34:49]
	s_waitcnt lgkmcnt(0)
	v_mfma_f32_32x32x16_bf16 v[18:33], v[126:129], v[82:85], v[18:33]
	ds_read_b128 v[66:69], v105 offset:55360
	ds_read_b128 v[70:73], v164 offset:55360
	ds_read_b128 v[82:85], v164 offset:55392
	ds_read_b128 v[86:89], v105 offset:55392
	s_waitcnt lgkmcnt(2)
	v_mfma_f32_32x32x16_bf16 v[50:65], v[66:69], v[70:73], v[50:65]
	ds_read_b128 v[66:69], v105 offset:59968
	ds_read_b128 v[110:113], v105 offset:60000
	s_waitcnt lgkmcnt(1)
	s_setprio 1
	v_mfma_f32_32x32x16_bf16 v[2:17], v[66:69], v[70:73], v[2:17]
	ds_read_b128 v[66:69], v104 offset:64
	ds_read_b128 v[114:117], v104 offset:96
	s_waitcnt lgkmcnt(1)
	v_mfma_f32_32x32x16_bf16 v[34:49], v[66:69], v[70:73], v[34:49]
	ds_read_b128 v[66:69], v104 offset:4672
	ds_read_b128 v[126:129], v104 offset:4704
	s_waitcnt lgkmcnt(1)
	v_mfma_f32_32x32x16_bf16 v[18:33], v[66:69], v[70:73], v[18:33]
	v_mfma_f32_32x32x16_bf16 v[50:65], v[86:89], v[82:85], v[50:65]
	v_mfma_f32_32x32x16_bf16 v[2:17], v[110:113], v[82:85], v[2:17]
	v_mfma_f32_32x32x16_bf16 v[34:49], v[114:117], v[82:85], v[34:49]
	s_setprio 0
	global_load_dwordx4 v[66:69], v[102:103], off offset:1152
	global_load_dwordx4 v[70:73], v[102:103], off offset:1216
	global_load_dwordx4 v[86:89], v[96:97], off offset:1152
	global_load_dwordx4 v[110:113], v[96:97], off offset:1216
	global_load_dwordx4 v[114:117], v[94:95], off offset:1152
	global_load_dwordx4 v[130:133], v[94:95], off offset:1216
	s_waitcnt vmcnt(11)
	ds_write_b128 v162, v[74:77]
	s_waitcnt vmcnt(10)
	ds_write_b128 v162, v[78:81] offset:64
	s_waitcnt vmcnt(9)
	ds_write_b128 v162, v[118:121] offset:18432
	s_waitcnt vmcnt(8)
	ds_write_b128 v162, v[122:125] offset:18496
	s_waitcnt vmcnt(7)
	ds_write_b128 v162, v[138:141] offset:36864
	s_waitcnt vmcnt(6)
	ds_write_b128 v162, v[142:145] offset:36928
	s_waitcnt lgkmcnt(0)
	s_barrier
	s_setprio 3
	v_mfma_f32_32x32x16_bf16 v[18:33], v[126:129], v[82:85], v[18:33]
	ds_read_b128 v[74:77], v163 offset:18432
	ds_read_b128 v[78:81], v164
	ds_read_b128 v[82:85], v164 offset:32
	ds_read_b128 v[118:121], v163 offset:18464
	s_waitcnt lgkmcnt(2)
	v_mfma_f32_32x32x16_bf16 v[50:65], v[74:77], v[78:81], v[50:65]
	ds_read_b128 v[74:77], v163 offset:23040
	ds_read_b128 v[122:125], v163 offset:23072
	s_waitcnt lgkmcnt(1)
	v_mfma_f32_32x32x16_bf16 v[2:17], v[74:77], v[78:81], v[2:17]
	ds_read_b128 v[74:77], v163 offset:36864
	ds_read_b128 v[126:129], v163 offset:36896
	s_waitcnt lgkmcnt(1)
	v_mfma_f32_32x32x16_bf16 v[34:49], v[74:77], v[78:81], v[34:49]
	ds_read_b128 v[74:77], v163 offset:41472
	ds_read_b128 v[134:137], v163 offset:41504
	s_waitcnt lgkmcnt(1)
	v_mfma_f32_32x32x16_bf16 v[18:33], v[74:77], v[78:81], v[18:33]
	s_setprio 2
	v_mfma_f32_32x32x16_bf16 v[50:65], v[118:121], v[82:85], v[50:65]
	v_mfma_f32_32x32x16_bf16 v[2:17], v[122:125], v[82:85], v[2:17]
	v_mfma_f32_32x32x16_bf16 v[34:49], v[126:129], v[82:85], v[34:49]
	s_waitcnt lgkmcnt(0)
	v_mfma_f32_32x32x16_bf16 v[18:33], v[134:137], v[82:85], v[18:33]
	ds_read_b128 v[74:77], v163 offset:18496
	ds_read_b128 v[78:81], v164 offset:64
	ds_read_b128 v[82:85], v164 offset:96
	ds_read_b128 v[118:121], v163 offset:18528
	s_waitcnt lgkmcnt(2)
	v_mfma_f32_32x32x16_bf16 v[50:65], v[74:77], v[78:81], v[50:65]
	ds_read_b128 v[74:77], v163 offset:23104
	ds_read_b128 v[122:125], v163 offset:23136
	s_waitcnt lgkmcnt(1)
	s_setprio 1
	v_mfma_f32_32x32x16_bf16 v[2:17], v[74:77], v[78:81], v[2:17]
	ds_read_b128 v[74:77], v163 offset:36928
	ds_read_b128 v[126:129], v163 offset:36960
	s_waitcnt lgkmcnt(1)
	v_mfma_f32_32x32x16_bf16 v[34:49], v[74:77], v[78:81], v[34:49]
	ds_read_b128 v[74:77], v163 offset:41536
	ds_read_b128 v[134:137], v163 offset:41568
	s_waitcnt lgkmcnt(1)
	v_mfma_f32_32x32x16_bf16 v[18:33], v[74:77], v[78:81], v[18:33]
	global_load_dwordx4 v[74:77], v[102:103], off offset:1280
	v_mfma_f32_32x32x16_bf16 v[50:65], v[118:121], v[82:85], v[50:65]
	v_mfma_f32_32x32x16_bf16 v[2:17], v[122:125], v[82:85], v[2:17]
	s_setprio 0
	global_load_dwordx4 v[78:81], v[102:103], off offset:1344
	global_load_dwordx4 v[118:121], v[96:97], off offset:1280
	global_load_dwordx4 v[122:125], v[96:97], off offset:1344
	global_load_dwordx4 v[138:141], v[94:95], off offset:1280
	global_load_dwordx4 v[142:145], v[94:95], off offset:1344
	s_waitcnt vmcnt(11)
	ds_write_b128 v162, v[66:69] offset:55296
	s_waitcnt vmcnt(10)
	ds_write_b128 v162, v[70:73] offset:55360
	s_waitcnt vmcnt(9)
	ds_write_b128 v108, v[86:89]
	s_waitcnt vmcnt(8)
	ds_write_b128 v108, v[110:113] offset:64
	s_waitcnt vmcnt(7)
	ds_write_b128 v107, v[114:117]
	s_waitcnt vmcnt(6)
	ds_write_b128 v107, v[130:133] offset:64
	s_waitcnt lgkmcnt(0)
	s_barrier
; __device__ __forceinline__ void p4_pass2(const bf16_t* __restrict__ A, int K, const bf16_t* __restrict__ B0, const bf16_t* __restrict__ B1, int rt, int ct, f32x16& a0, f32x16& a1, f32x16& m0, f32x16& m1, LAS char* lds, int tid, int r32, int hi, int wa, int wb) {
;     ...
;     for (int kt = 0; kt < nk; kt += 2) { P4_STEP2(kt, rA, rB); P4_STEP2(kt + 1, rB, rA); }
	s_setprio 3
	v_mfma_f32_32x32x16_bf16 v[34:49], v[126:129], v[82:85], v[34:49]
	v_mfma_f32_32x32x16_bf16 v[18:33], v[134:137], v[82:85], v[18:33]
	ds_read_b128 v[66:69], v105 offset:55296
	ds_read_b128 v[70:73], v164 offset:55296
	ds_read_b128 v[82:85], v164 offset:55328
	ds_read_b128 v[86:89], v105 offset:55328
	s_waitcnt lgkmcnt(2)
	v_mfma_f32_32x32x16_bf16 v[50:65], v[66:69], v[70:73], v[50:65]
	ds_read_b128 v[66:69], v105 offset:59904
	ds_read_b128 v[110:113], v105 offset:59936
	s_waitcnt lgkmcnt(1)
	v_mfma_f32_32x32x16_bf16 v[2:17], v[66:69], v[70:73], v[2:17]
	ds_read_b128 v[66:69], v104
	ds_read_b128 v[114:117], v104 offset:32
	s_waitcnt lgkmcnt(1)
	v_mfma_f32_32x32x16_bf16 v[34:49], v[66:69], v[70:73], v[34:49]
	ds_read_b128 v[66:69], v104 offset:4608
	ds_read_b128 v[126:129], v104 offset:4640
	s_waitcnt lgkmcnt(1)
	s_setprio 2
	v_mfma_f32_32x32x16_bf16 v[18:33], v[66:69], v[70:73], v[18:33]
	v_mfma_f32_32x32x16_bf16 v[50:65], v[86:89], v[82:85], v[50:65]
	v_mfma_f32_32x32x16_bf16 v[2:17], v[110:113], v[82:85], v[2:17]
	v_mfma_f32_32x32x16_bf16 v[34:49], v[114:117], v[82:85], v[34:49]
	s_waitcnt lgkmcnt(0)
	v_mfma_f32_32x32x16_bf16 v[18:33], v[126:129], v[82:85], v[18:33]
	ds_read_b128 v[66:69], v105 offset:55360
	ds_read_b128 v[70:73], v164 offset:55360
	ds_read_b128 v[82:85], v164 offset:55392
	ds_read_b128 v[86:89], v105 offset:55392
	s_waitcnt lgkmcnt(2)
	v_mfma_f32_32x32x16_bf16 v[50:65], v[66:69], v[70:73], v[50:65]
	ds_read_b128 v[66:69], v105 offset:59968
	ds_read_b128 v[110:113], v105 offset:60000
	s_waitcnt lgkmcnt(1)
	s_setprio 1
	v_mfma_f32_32x32x16_bf16 v[2:17], v[66:69], v[70:73], v[2:17]
	ds_read_b128 v[66:69], v104 offset:64
	ds_read_b128 v[114:117], v104 offset:96
	s_waitcnt lgkmcnt(1)
	v_mfma_f32_32x32x16_bf16 v[34:49], v[66:69], v[70:73], v[34:49]
	ds_read_b128 v[66:69], v104 offset:4672
	ds_read_b128 v[126:129], v104 offset:4704
	s_waitcnt lgkmcnt(1)
	v_mfma_f32_32x32x16_bf16 v[18:33], v[66:69], v[70:73], v[18:33]
	v_mfma_f32_32x32x16_bf16 v[50:65], v[86:89], v[82:85], v[50:65]
	v_mfma_f32_32x32x16_bf16 v[2:17], v[110:113], v[82:85], v[2:17]
	v_mfma_f32_32x32x16_bf16 v[34:49], v[114:117], v[82:85], v[34:49]
	s_setprio 0
	global_load_dwordx4 v[66:69], v[102:103], off offset:1408
	global_load_dwordx4 v[70:73], v[102:103], off offset:1472
	global_load_dwordx4 v[86:89], v[96:97], off offset:1408
	global_load_dwordx4 v[110:113], v[96:97], off offset:1472
	global_load_dwordx4 v[114:117], v[94:95], off offset:1408
	global_load_dwordx4 v[130:133], v[94:95], off offset:1472
	s_waitcnt vmcnt(11)
	ds_write_b128 v162, v[74:77]
	s_waitcnt vmcnt(10)
	ds_write_b128 v162, v[78:81] offset:64
	s_waitcnt vmcnt(9)
	ds_write_b128 v162, v[118:121] offset:18432
	s_waitcnt vmcnt(8)
	ds_write_b128 v162, v[122:125] offset:18496
	s_waitcnt vmcnt(7)
	ds_write_b128 v162, v[138:141] offset:36864
	s_waitcnt vmcnt(6)
	ds_write_b128 v162, v[142:145] offset:36928
	s_waitcnt lgkmcnt(0)
	s_barrier
	s_setprio 3
	v_mfma_f32_32x32x16_bf16 v[18:33], v[126:129], v[82:85], v[18:33]
	ds_read_b128 v[74:77], v163 offset:18432
	ds_read_b128 v[78:81], v164
	ds_read_b128 v[82:85], v164 offset:32
	ds_read_b128 v[118:121], v163 offset:18464
	s_waitcnt lgkmcnt(2)
	v_mfma_f32_32x32x16_bf16 v[50:65], v[74:77], v[78:81], v[50:65]
	ds_read_b128 v[74:77], v163 offset:23040
	ds_read_b128 v[122:125], v163 offset:23072
	s_waitcnt lgkmcnt(1)
	v_mfma_f32_32x32x16_bf16 v[2:17], v[74:77], v[78:81], v[2:17]
	ds_read_b128 v[74:77], v163 offset:36864
	ds_read_b128 v[126:129], v163 offset:36896
	s_waitcnt lgkmcnt(1)
	v_mfma_f32_32x32x16_bf16 v[34:49], v[74:77], v[78:81], v[34:49]
	ds_read_b128 v[74:77], v163 offset:41472
	ds_read_b128 v[134:137], v163 offset:41504
	s_waitcnt lgkmcnt(1)
	v_mfma_f32_32x32x16_bf16 v[18:33], v[74:77], v[78:81], v[18:33]
	s_setprio 2
	v_mfma_f32_32x32x16_bf16 v[50:65], v[118:121], v[82:85], v[50:65]
	v_mfma_f32_32x32x16_bf16 v[2:17], v[122:125], v[82:85], v[2:17]
	v_mfma_f32_32x32x16_bf16 v[34:49], v[126:129], v[82:85], v[34:49]
	s_waitcnt lgkmcnt(0)
	v_mfma_f32_32x32x16_bf16 v[18:33], v[134:137], v[82:85], v[18:33]
	ds_read_b128 v[74:77], v163 offset:18496
	ds_read_b128 v[78:81], v164 offset:64
	ds_read_b128 v[82:85], v164 offset:96
	ds_read_b128 v[118:121], v163 offset:18528
	s_waitcnt lgkmcnt(2)
	v_mfma_f32_32x32x16_bf16 v[50:65], v[74:77], v[78:81], v[50:65]
	ds_read_b128 v[74:77], v163 offset:23104
	ds_read_b128 v[122:125], v163 offset:23136
	s_waitcnt lgkmcnt(1)
	s_setprio 1
	v_mfma_f32_32x32x16_bf16 v[2:17], v[74:77], v[78:81], v[2:17]
	ds_read_b128 v[74:77], v163 offset:36928
	ds_read_b128 v[126:129], v163 offset:36960
	s_waitcnt lgkmcnt(1)
	v_mfma_f32_32x32x16_bf16 v[34:49], v[74:77], v[78:81], v[34:49]
	ds_read_b128 v[74:77], v163 offset:41536
	ds_read_b128 v[134:137], v163 offset:41568
	s_waitcnt lgkmcnt(1)
	v_mfma_f32_32x32x16_bf16 v[18:33], v[74:77], v[78:81], v[18:33]
	global_load_dwordx4 v[74:77], v[102:103], off offset:1536
	v_mfma_f32_32x32x16_bf16 v[50:65], v[118:121], v[82:85], v[50:65]
	v_mfma_f32_32x32x16_bf16 v[2:17], v[122:125], v[82:85], v[2:17]
	s_setprio 0
	global_load_dwordx4 v[78:81], v[102:103], off offset:1600
	global_load_dwordx4 v[118:121], v[96:97], off offset:1536
	global_load_dwordx4 v[122:125], v[96:97], off offset:1600
	global_load_dwordx4 v[138:141], v[94:95], off offset:1536
	global_load_dwordx4 v[142:145], v[94:95], off offset:1600
	s_waitcnt vmcnt(11)
	ds_write_b128 v162, v[66:69] offset:55296
	s_waitcnt vmcnt(10)
	ds_write_b128 v162, v[70:73] offset:55360
	s_waitcnt vmcnt(9)
	ds_write_b128 v108, v[86:89]
	s_waitcnt vmcnt(8)
	ds_write_b128 v108, v[110:113] offset:64
	s_waitcnt vmcnt(7)
	ds_write_b128 v107, v[114:117]
	s_waitcnt vmcnt(6)
	ds_write_b128 v107, v[130:133] offset:64
	s_waitcnt lgkmcnt(0)
	s_barrier
; __device__ __forceinline__ void p4_pass2(const bf16_t* __restrict__ A, int K, const bf16_t* __restrict__ B0, const bf16_t* __restrict__ B1, int rt, int ct, f32x16& a0, f32x16& a1, f32x16& m0, f32x16& m1, LAS char* lds, int tid, int r32, int hi, int wa, int wb) {
;     ...
;     for (int kt = 0; kt < nk; kt += 2) { P4_STEP2(kt, rA, rB); P4_STEP2(kt + 1, rB, rA); }
	s_setprio 3
	v_mfma_f32_32x32x16_bf16 v[34:49], v[126:129], v[82:85], v[34:49]
	v_mfma_f32_32x32x16_bf16 v[18:33], v[134:137], v[82:85], v[18:33]
	ds_read_b128 v[66:69], v105 offset:55296
	ds_read_b128 v[70:73], v164 offset:55296
	ds_read_b128 v[82:85], v164 offset:55328
	ds_read_b128 v[86:89], v105 offset:55328
	s_waitcnt lgkmcnt(2)
	v_mfma_f32_32x32x16_bf16 v[50:65], v[66:69], v[70:73], v[50:65]
	ds_read_b128 v[66:69], v105 offset:59904
	ds_read_b128 v[110:113], v105 offset:59936
	s_waitcnt lgkmcnt(1)
	v_mfma_f32_32x32x16_bf16 v[2:17], v[66:69], v[70:73], v[2:17]
	ds_read_b128 v[66:69], v104
	ds_read_b128 v[114:117], v104 offset:32
	s_waitcnt lgkmcnt(1)
	v_mfma_f32_32x32x16_bf16 v[34:49], v[66:69], v[70:73], v[34:49]
	ds_read_b128 v[66:69], v104 offset:4608
	ds_read_b128 v[126:129], v104 offset:4640
	s_waitcnt lgkmcnt(1)
	s_setprio 2
	v_mfma_f32_32x32x16_bf16 v[18:33], v[66:69], v[70:73], v[18:33]
	v_mfma_f32_32x32x16_bf16 v[50:65], v[86:89], v[82:85], v[50:65]
	v_mfma_f32_32x32x16_bf16 v[2:17], v[110:113], v[82:85], v[2:17]
	v_mfma_f32_32x32x16_bf16 v[34:49], v[114:117], v[82:85], v[34:49]
	s_waitcnt lgkmcnt(0)
	v_mfma_f32_32x32x16_bf16 v[18:33], v[126:129], v[82:85], v[18:33]
	ds_read_b128 v[66:69], v105 offset:55360
	ds_read_b128 v[70:73], v164 offset:55360
	ds_read_b128 v[82:85], v164 offset:55392
	ds_read_b128 v[86:89], v105 offset:55392
	s_waitcnt lgkmcnt(2)
	v_mfma_f32_32x32x16_bf16 v[50:65], v[66:69], v[70:73], v[50:65]
	ds_read_b128 v[66:69], v105 offset:59968
	ds_read_b128 v[110:113], v105 offset:60000
	s_waitcnt lgkmcnt(1)
	s_setprio 1
	v_mfma_f32_32x32x16_bf16 v[2:17], v[66:69], v[70:73], v[2:17]
	ds_read_b128 v[66:69], v104 offset:64
	ds_read_b128 v[114:117], v104 offset:96
	s_waitcnt lgkmcnt(1)
	v_mfma_f32_32x32x16_bf16 v[34:49], v[66:69], v[70:73], v[34:49]
	ds_read_b128 v[66:69], v104 offset:4672
	ds_read_b128 v[126:129], v104 offset:4704
	s_waitcnt lgkmcnt(1)
	v_mfma_f32_32x32x16_bf16 v[18:33], v[66:69], v[70:73], v[18:33]
	v_mfma_f32_32x32x16_bf16 v[50:65], v[86:89], v[82:85], v[50:65]
	v_mfma_f32_32x32x16_bf16 v[2:17], v[110:113], v[82:85], v[2:17]
	v_mfma_f32_32x32x16_bf16 v[34:49], v[114:117], v[82:85], v[34:49]
	s_setprio 0
	global_load_dwordx4 v[66:69], v[102:103], off offset:1664
	global_load_dwordx4 v[70:73], v[102:103], off offset:1728
	global_load_dwordx4 v[86:89], v[96:97], off offset:1664
	global_load_dwordx4 v[110:113], v[96:97], off offset:1728
	global_load_dwordx4 v[114:117], v[94:95], off offset:1664
	global_load_dwordx4 v[130:133], v[94:95], off offset:1728
	s_waitcnt vmcnt(11)
	ds_write_b128 v162, v[74:77]
	s_waitcnt vmcnt(10)
	ds_write_b128 v162, v[78:81] offset:64
	s_waitcnt vmcnt(9)
	ds_write_b128 v162, v[118:121] offset:18432
	s_waitcnt vmcnt(8)
	ds_write_b128 v162, v[122:125] offset:18496
	s_waitcnt vmcnt(7)
	ds_write_b128 v162, v[138:141] offset:36864
	s_waitcnt vmcnt(6)
	ds_write_b128 v162, v[142:145] offset:36928
	s_waitcnt lgkmcnt(0)
	s_barrier
	s_setprio 3
	v_mfma_f32_32x32x16_bf16 v[18:33], v[126:129], v[82:85], v[18:33]
	ds_read_b128 v[74:77], v163 offset:18432
	ds_read_b128 v[78:81], v164
	ds_read_b128 v[82:85], v164 offset:32
	ds_read_b128 v[118:121], v163 offset:18464
	s_waitcnt lgkmcnt(2)
	v_mfma_f32_32x32x16_bf16 v[50:65], v[74:77], v[78:81], v[50:65]
	ds_read_b128 v[74:77], v163 offset:23040
	ds_read_b128 v[122:125], v163 offset:23072
	s_waitcnt lgkmcnt(1)
	v_mfma_f32_32x32x16_bf16 v[2:17], v[74:77], v[78:81], v[2:17]
	ds_read_b128 v[74:77], v163 offset:36864
	ds_read_b128 v[126:129], v163 offset:36896
	s_waitcnt lgkmcnt(1)
	v_mfma_f32_32x32x16_bf16 v[34:49], v[74:77], v[78:81], v[34:49]
	ds_read_b128 v[74:77], v163 offset:41472
	ds_read_b128 v[134:137], v163 offset:41504
	s_waitcnt lgkmcnt(1)
	v_mfma_f32_32x32x16_bf16 v[18:33], v[74:77], v[78:81], v[18:33]
	s_setprio 2
	v_mfma_f32_32x32x16_bf16 v[50:65], v[118:121], v[82:85], v[50:65]
	v_mfma_f32_32x32x16_bf16 v[2:17], v[122:125], v[82:85], v[2:17]
	v_mfma_f32_32x32x16_bf16 v[34:49], v[126:129], v[82:85], v[34:49]
	s_waitcnt lgkmcnt(0)
	v_mfma_f32_32x32x16_bf16 v[18:33], v[134:137], v[82:85], v[18:33]
	ds_read_b128 v[74:77], v163 offset:18496
	ds_read_b128 v[78:81], v164 offset:64
	ds_read_b128 v[82:85], v164 offset:96
	ds_read_b128 v[118:121], v163 offset:18528
	s_waitcnt lgkmcnt(2)
	v_mfma_f32_32x32x16_bf16 v[50:65], v[74:77], v[78:81], v[50:65]
	ds_read_b128 v[74:77], v163 offset:23104
	ds_read_b128 v[122:125], v163 offset:23136
	s_waitcnt lgkmcnt(1)
	s_setprio 1
	v_mfma_f32_32x32x16_bf16 v[2:17], v[74:77], v[78:81], v[2:17]
	ds_read_b128 v[74:77], v163 offset:36928
	ds_read_b128 v[126:129], v163 offset:36960
	s_waitcnt lgkmcnt(1)
	v_mfma_f32_32x32x16_bf16 v[34:49], v[74:77], v[78:81], v[34:49]
	ds_read_b128 v[74:77], v163 offset:41536
	ds_read_b128 v[134:137], v163 offset:41568
	s_waitcnt lgkmcnt(1)
	v_mfma_f32_32x32x16_bf16 v[18:33], v[74:77], v[78:81], v[18:33]
	global_load_dwordx4 v[74:77], v[102:103], off offset:1792
	v_mfma_f32_32x32x16_bf16 v[50:65], v[118:121], v[82:85], v[50:65]
	v_mfma_f32_32x32x16_bf16 v[2:17], v[122:125], v[82:85], v[2:17]
	s_setprio 0
	global_load_dwordx4 v[78:81], v[102:103], off offset:1856
	global_load_dwordx4 v[118:121], v[96:97], off offset:1792
	global_load_dwordx4 v[122:125], v[96:97], off offset:1856
	global_load_dwordx4 v[138:141], v[94:95], off offset:1792
	global_load_dwordx4 v[142:145], v[94:95], off offset:1856
	s_waitcnt vmcnt(11)
	ds_write_b128 v162, v[66:69] offset:55296
	s_waitcnt vmcnt(10)
	ds_write_b128 v162, v[70:73] offset:55360
	s_waitcnt vmcnt(9)
	ds_write_b128 v108, v[86:89]
	s_waitcnt vmcnt(8)
	ds_write_b128 v108, v[110:113] offset:64
	s_waitcnt vmcnt(7)
	ds_write_b128 v107, v[114:117]
	s_waitcnt vmcnt(6)
	ds_write_b128 v107, v[130:133] offset:64
	s_waitcnt lgkmcnt(0)
	s_barrier
; __device__ __forceinline__ void p4_pass2(const bf16_t* __restrict__ A, int K, const bf16_t* __restrict__ B0, const bf16_t* __restrict__ B1, int rt, int ct, f32x16& a0, f32x16& a1, f32x16& m0, f32x16& m1, LAS char* lds, int tid, int r32, int hi, int wa, int wb) {
;     ...
;     for (int kt = 0; kt < nk; kt += 2) { P4_STEP2(kt, rA, rB); P4_STEP2(kt + 1, rB, rA); }
	s_setprio 3
	v_mfma_f32_32x32x16_bf16 v[34:49], v[126:129], v[82:85], v[34:49]
	v_mfma_f32_32x32x16_bf16 v[18:33], v[134:137], v[82:85], v[18:33]
	ds_read_b128 v[66:69], v105 offset:55296
	ds_read_b128 v[70:73], v164 offset:55296
	ds_read_b128 v[82:85], v164 offset:55328
	ds_read_b128 v[86:89], v105 offset:55328
	s_waitcnt lgkmcnt(2)
	v_mfma_f32_32x32x16_bf16 v[50:65], v[66:69], v[70:73], v[50:65]
	ds_read_b128 v[66:69], v105 offset:59904
	ds_read_b128 v[110:113], v105 offset:59936
	s_waitcnt lgkmcnt(1)
	v_mfma_f32_32x32x16_bf16 v[2:17], v[66:69], v[70:73], v[2:17]
	ds_read_b128 v[66:69], v104
	ds_read_b128 v[114:117], v104 offset:32
	s_waitcnt lgkmcnt(1)
	v_mfma_f32_32x32x16_bf16 v[34:49], v[66:69], v[70:73], v[34:49]
	ds_read_b128 v[66:69], v104 offset:4608
	ds_read_b128 v[126:129], v104 offset:4640
	s_waitcnt lgkmcnt(1)
	s_setprio 2
	v_mfma_f32_32x32x16_bf16 v[18:33], v[66:69], v[70:73], v[18:33]
	v_mfma_f32_32x32x16_bf16 v[50:65], v[86:89], v[82:85], v[50:65]
	v_mfma_f32_32x32x16_bf16 v[2:17], v[110:113], v[82:85], v[2:17]
	v_mfma_f32_32x32x16_bf16 v[34:49], v[114:117], v[82:85], v[34:49]
	s_waitcnt lgkmcnt(0)
	v_mfma_f32_32x32x16_bf16 v[18:33], v[126:129], v[82:85], v[18:33]
	ds_read_b128 v[66:69], v105 offset:55360
	ds_read_b128 v[70:73], v164 offset:55360
	ds_read_b128 v[82:85], v164 offset:55392
	ds_read_b128 v[86:89], v105 offset:55392
	s_waitcnt lgkmcnt(2)
	v_mfma_f32_32x32x16_bf16 v[50:65], v[66:69], v[70:73], v[50:65]
	ds_read_b128 v[66:69], v105 offset:59968
	ds_read_b128 v[110:113], v105 offset:60000
	s_waitcnt lgkmcnt(1)
	s_setprio 1
	v_mfma_f32_32x32x16_bf16 v[2:17], v[66:69], v[70:73], v[2:17]
	ds_read_b128 v[66:69], v104 offset:64
	ds_read_b128 v[114:117], v104 offset:96
	s_waitcnt lgkmcnt(1)
	v_mfma_f32_32x32x16_bf16 v[34:49], v[66:69], v[70:73], v[34:49]
	ds_read_b128 v[66:69], v104 offset:4672
	ds_read_b128 v[126:129], v104 offset:4704
	s_waitcnt lgkmcnt(1)
	v_mfma_f32_32x32x16_bf16 v[18:33], v[66:69], v[70:73], v[18:33]
	v_mfma_f32_32x32x16_bf16 v[50:65], v[86:89], v[82:85], v[50:65]
	v_mfma_f32_32x32x16_bf16 v[2:17], v[110:113], v[82:85], v[2:17]
	v_mfma_f32_32x32x16_bf16 v[34:49], v[114:117], v[82:85], v[34:49]
	s_setprio 0
	global_load_dwordx4 v[66:69], v[102:103], off offset:1920
	global_load_dwordx4 v[70:73], v[102:103], off offset:1984
	global_load_dwordx4 v[86:89], v[96:97], off offset:1920
	global_load_dwordx4 v[110:113], v[96:97], off offset:1984
	global_load_dwordx4 v[114:117], v[94:95], off offset:1920
	s_nop 0
	global_load_dwordx4 v[94:97], v[94:95], off offset:1984
	s_waitcnt vmcnt(11)
	ds_write_b128 v162, v[74:77]
	s_waitcnt vmcnt(10)
	ds_write_b128 v162, v[78:81] offset:64
	s_waitcnt vmcnt(9)
	ds_write_b128 v162, v[118:121] offset:18432
	s_waitcnt vmcnt(8)
	ds_write_b128 v162, v[122:125] offset:18496
	s_waitcnt vmcnt(7)
	ds_write_b128 v162, v[138:141] offset:36864
	s_waitcnt vmcnt(6)
	ds_write_b128 v162, v[142:145] offset:36928
	s_waitcnt lgkmcnt(0)
	s_barrier
	s_setprio 3
	v_mfma_f32_32x32x16_bf16 v[18:33], v[126:129], v[82:85], v[18:33]
	ds_read_b128 v[74:77], v163 offset:18432
	ds_read_b128 v[78:81], v164
	ds_read_b128 v[82:85], v164 offset:32
	ds_read_b128 v[118:121], v163 offset:18464
	s_waitcnt lgkmcnt(2)
	v_mfma_f32_32x32x16_bf16 v[50:65], v[74:77], v[78:81], v[50:65]
	ds_read_b128 v[74:77], v163 offset:23040
	ds_read_b128 v[122:125], v163 offset:23072
	s_waitcnt lgkmcnt(1)
	v_mfma_f32_32x32x16_bf16 v[2:17], v[74:77], v[78:81], v[2:17]
	ds_read_b128 v[74:77], v163 offset:36864
	ds_read_b128 v[126:129], v163 offset:36896
	s_waitcnt lgkmcnt(1)
	v_mfma_f32_32x32x16_bf16 v[34:49], v[74:77], v[78:81], v[34:49]
	ds_read_b128 v[74:77], v163 offset:41472
	ds_read_b128 v[130:133], v163 offset:41504
	s_waitcnt lgkmcnt(1)
	s_setprio 2
	v_mfma_f32_32x32x16_bf16 v[18:33], v[74:77], v[78:81], v[18:33]
	v_mfma_f32_32x32x16_bf16 v[50:65], v[118:121], v[82:85], v[50:65]
	v_mfma_f32_32x32x16_bf16 v[2:17], v[122:125], v[82:85], v[2:17]
	v_mfma_f32_32x32x16_bf16 v[34:49], v[126:129], v[82:85], v[34:49]
	s_waitcnt lgkmcnt(0)
	s_setprio 1
	v_mfma_f32_32x32x16_bf16 v[18:33], v[130:133], v[82:85], v[18:33]
	ds_read_b128 v[74:77], v163 offset:18496
	ds_read_b128 v[78:81], v164 offset:64
	ds_read_b128 v[82:85], v164 offset:96
	ds_read_b128 v[118:121], v163 offset:18528
	s_waitcnt lgkmcnt(2)
	v_mfma_f32_32x32x16_bf16 v[50:65], v[74:77], v[78:81], v[50:65]
	ds_read_b128 v[74:77], v163 offset:23104
	ds_read_b128 v[122:125], v163 offset:23136
	s_waitcnt lgkmcnt(1)
	v_mfma_f32_32x32x16_bf16 v[2:17], v[74:77], v[78:81], v[2:17]
	ds_read_b128 v[74:77], v163 offset:36928
	ds_read_b128 v[126:129], v163 offset:36960
	s_waitcnt lgkmcnt(1)
	v_mfma_f32_32x32x16_bf16 v[34:49], v[74:77], v[78:81], v[34:49]
	s_setprio 0
	ds_read_b128 v[74:77], v163 offset:41536
	ds_read_b128 v[130:133], v163 offset:41568
	s_waitcnt vmcnt(5)
	ds_write_b128 v162, v[66:69] offset:55296
	s_waitcnt vmcnt(4)
	ds_write_b128 v162, v[70:73] offset:55360
	s_waitcnt vmcnt(3)
	ds_write_b128 v108, v[86:89]
	s_waitcnt vmcnt(2)
	ds_write_b128 v108, v[110:113] offset:64
	s_waitcnt vmcnt(1)
	ds_write_b128 v107, v[114:117]
	s_waitcnt vmcnt(0)
	ds_write_b128 v107, v[94:97] offset:64
	s_waitcnt lgkmcnt(0)
	s_barrier
; #define LAS __attribute__((address_space(3)))
; __device__ __forceinline__ void p4_pass(const bf16_t* __restrict__ A, int K, const bf16_t* __restrict__ B, int rt, int ct, f32x16& c0, f32x16& c1, LAS char* lds, int tid, int r32, int hi, int wa, int wb) {
;     const bf16_t* asrc = A + (size_t)(rt * 128 + (tid >> 2)) * K + (tid & 3) * 8;
;     const bf16_t* bsrc = B + (size_t)(ct * 128 + (tid >> 2)) * K + (tid & 3) * 8;
;     const int sdst = (tid >> 2) * P4_PITCH + (tid & 3) * 16;
;     const int xoff = (wa * 32 + r32) * P4_PITCH + hi * 16, woff = P4_OPB + (wb * 64 + r32) * P4_PITCH + hi * 16;
;     const int nk = K >> 6;
;     u32x4 ga0 = *(const u32x4*)asrc, ha0 = *(const u32x4*)(asrc + 32), gb0 = *(const u32x4*)bsrc, hb0 = *(const u32x4*)(bsrc + 32), ga1, ha1, gb1, hb1;
;     *(LAS u32x4*)(lds + sdst) = ga0; *(LAS u32x4*)(lds + sdst + 64) = ha0; *(LAS u32x4*)(lds + P4_OPB + sdst) = gb0; *(LAS u32x4*)(lds + P4_OPB + sdst + 64) = hb0;
;     ga1 = *(const u32x4*)(asrc + 64); ha1 = *(const u32x4*)(asrc + 96); gb1 = *(const u32x4*)(bsrc + 64); hb1 = *(const u32x4*)(bsrc + 96);
;     __syncthreads();
;     c0 = (f32x16){}; c1 = (f32x16){};
;     ...
;     for (int kt = 0; kt < nk; kt += 2) {
;         P4_STEP(kt, ga0, ha0, gb0, hb0, ga1, ha1, gb1, hb1);
;         P4_STEP(kt + 1, ga1, ha1, gb1, hb1, ga0, ha0, gb0, hb0);
; __device__ __forceinline__ void p4_pass2(const bf16_t* __restrict__ A, int K, const bf16_t* __restrict__ B0, const bf16_t* __restrict__ B1, int rt, int ct, f32x16& a0, f32x16& a1, f32x16& m0, f32x16& m1, LAS char* lds, int tid, int r32, int hi, int wa, int wb) {
;     ...
;     for (int kt = 0; kt < nk; kt += 2) { P4_STEP2(kt, rA, rB); P4_STEP2(kt + 1, rB, rA); }
	s_setprio 3
	v_mfma_f32_32x32x16_bf16 v[18:33], v[74:77], v[78:81], v[18:33]
	ds_read_b128 v[66:69], v105 offset:55296
	ds_read_b128 v[70:73], v164 offset:55296
	ds_read_b128 v[74:77], v164 offset:55328
	ds_read_b128 v[78:81], v105 offset:55328
	v_mfma_f32_32x32x16_bf16 v[50:65], v[118:121], v[82:85], v[50:65]
	v_mfma_f32_32x32x16_bf16 v[2:17], v[122:125], v[82:85], v[2:17]
	v_mfma_f32_32x32x16_bf16 v[34:49], v[126:129], v[82:85], v[34:49]
	v_mfma_f32_32x32x16_bf16 v[18:33], v[130:133], v[82:85], v[18:33]
	s_waitcnt lgkmcnt(2)
	s_setprio 2
	v_mfma_f32_32x32x16_bf16 v[50:65], v[66:69], v[70:73], v[50:65]
	ds_read_b128 v[66:69], v105 offset:59904
	ds_read_b128 v[82:85], v105 offset:59936
	s_waitcnt lgkmcnt(1)
	v_mfma_f32_32x32x16_bf16 v[2:17], v[66:69], v[70:73], v[2:17]
	ds_read_b128 v[66:69], v104
	ds_read_b128 v[86:89], v104 offset:32
	s_waitcnt lgkmcnt(1)
	v_mfma_f32_32x32x16_bf16 v[34:49], v[66:69], v[70:73], v[34:49]
	ds_read_b128 v[66:69], v104 offset:4608
	ds_read_b128 v[94:97], v104 offset:4640
	s_waitcnt lgkmcnt(1)
	v_mfma_f32_32x32x16_bf16 v[18:33], v[66:69], v[70:73], v[18:33]
	v_mfma_f32_32x32x16_bf16 v[50:65], v[78:81], v[74:77], v[50:65]
	s_setprio 1
	v_mfma_f32_32x32x16_bf16 v[2:17], v[82:85], v[74:77], v[2:17]
	v_mfma_f32_32x32x16_bf16 v[34:49], v[86:89], v[74:77], v[34:49]
	s_waitcnt lgkmcnt(0)
	v_mfma_f32_32x32x16_bf16 v[18:33], v[94:97], v[74:77], v[18:33]
	ds_read_b128 v[66:69], v105 offset:55360
	ds_read_b128 v[70:73], v164 offset:55360
	ds_read_b128 v[74:77], v164 offset:55392
	ds_read_b128 v[78:81], v105 offset:55392
	s_waitcnt lgkmcnt(2)
	v_mfma_f32_32x32x16_bf16 v[50:65], v[66:69], v[70:73], v[50:65]
	ds_read_b128 v[66:69], v105 offset:59968
	ds_read_b128 v[82:85], v105 offset:60000
	s_waitcnt lgkmcnt(1)
	v_mfma_f32_32x32x16_bf16 v[2:17], v[66:69], v[70:73], v[2:17]
	ds_read_b128 v[66:69], v104 offset:64
	ds_read_b128 v[86:89], v104 offset:96
	s_waitcnt lgkmcnt(1)
	v_mfma_f32_32x32x16_bf16 v[34:49], v[66:69], v[70:73], v[34:49]
	s_setprio 0
	ds_read_b128 v[66:69], v104 offset:4672
	ds_read_b128 v[94:97], v104 offset:4704
	s_waitcnt lgkmcnt(0)
	s_barrier
	v_mfma_f32_32x32x16_bf16 v[18:33], v[66:69], v[70:73], v[18:33]
	v_lshlrev_b64 v[68:69], 10, v[90:91]
	v_lshlrev_b64 v[66:67], 10, v[92:93]
	v_lshl_add_u64 v[68:69], s[8:9], 0, v[68:69]
	v_lshl_add_u64 v[66:67], s[18:19], 0, v[66:67]
	v_lshl_add_u64 v[102:103], v[68:69], 0, v[0:1]
	v_lshl_add_u64 v[104:105], v[66:67], 0, v[0:1]
	v_lshlrev_b32_e32 v0, 3, v165
	v_mfma_f32_32x32x16_bf16 v[50:65], v[78:81], v[74:77], v[50:65]
	global_load_dwordx4 v[66:69], v[102:103], off
	global_load_dwordx4 v[70:73], v[102:103], off offset:64
	global_load_dwordx4 v[78:81], v[104:105], off
	v_mfma_f32_32x32x16_bf16 v[2:17], v[82:85], v[74:77], v[2:17]
	global_load_dwordx4 v[82:85], v[104:105], off offset:64
	global_load_dwordx4 v[106:109], v[102:103], off offset:128
	global_load_dwordx4 v[110:113], v[102:103], off offset:192
	global_load_dwordx4 v[114:117], v[104:105], off offset:128
	global_load_dwordx4 v[118:121], v[104:105], off offset:192
	s_waitcnt vmcnt(7)
	ds_write_b128 v162, v[66:69]
	s_waitcnt vmcnt(6)
	ds_write_b128 v162, v[70:73] offset:64
	s_waitcnt vmcnt(5)
	ds_write_b128 v162, v[78:81] offset:18432
	s_waitcnt vmcnt(4)
	ds_write_b128 v162, v[82:85] offset:18496
	s_waitcnt lgkmcnt(0)
	s_barrier
	s_setprio 3
	ds_read_b128 v[66:69], v163 offset:18432
	ds_read_b128 v[70:73], v164
	ds_read_b128 v[122:125], v164 offset:32
	ds_read_b128 v[126:129], v163 offset:18464
	v_mfma_f32_32x32x16_bf16 v[34:49], v[86:89], v[74:77], v[34:49]
	v_mul_f32_e32 v165, 0xbfb8aa3b, v51
	v_mul_f32_e32 v200, 0xbfb8aa3b, v52
	v_mul_f32_e32 v201, 0xbfb8aa3b, v53
	v_mul_f32_e32 v205, 0xbfb8aa3b, v54
	v_mfma_f32_32x32x16_bf16 v[18:33], v[94:97], v[74:77], v[18:33]
	s_waitcnt lgkmcnt(2)
	s_setprio 2
	v_mfma_f32_32x32x16_bf16 v[82:97], v[66:69], v[70:73], 0
	ds_read_b128 v[66:69], v163 offset:23040
	ds_read_b128 v[130:133], v163 offset:23072
	s_waitcnt lgkmcnt(1)
	v_mfma_f32_32x32x16_bf16 v[66:81], v[66:69], v[70:73], 0
	v_mfma_f32_32x32x16_bf16 v[82:97], v[126:129], v[122:125], v[82:97]
	s_waitcnt lgkmcnt(0)
	s_setprio 1
	v_mfma_f32_32x32x16_bf16 v[66:81], v[130:133], v[122:125], v[66:81]
	ds_read_b128 v[122:125], v163 offset:18496
	ds_read_b128 v[126:129], v164 offset:64
	ds_read_b128 v[130:133], v164 offset:96
	ds_read_b128 v[134:137], v163 offset:18528
	s_waitcnt lgkmcnt(2)
	v_mfma_f32_32x32x16_bf16 v[82:97], v[122:125], v[126:129], v[82:97]
	ds_read_b128 v[122:125], v163 offset:23104
	ds_read_b128 v[138:141], v163 offset:23136
	s_waitcnt lgkmcnt(1)
	v_mfma_f32_32x32x16_bf16 v[66:81], v[122:125], v[126:129], v[66:81]
	s_setprio 0
	global_load_dwordx4 v[122:125], v[102:103], off offset:256
	global_load_dwordx4 v[126:129], v[102:103], off offset:320
	global_load_dwordx4 v[142:145], v[104:105], off offset:256
	global_load_dwordx4 v[146:149], v[104:105], off offset:320
	s_waitcnt vmcnt(7)
	ds_write_b128 v162, v[106:109] offset:36864
	s_waitcnt vmcnt(6)
	ds_write_b128 v162, v[110:113] offset:36928
	s_waitcnt vmcnt(5)
	ds_write_b128 v162, v[114:117] offset:55296
	s_waitcnt vmcnt(4)
	ds_write_b128 v162, v[118:121] offset:55360
	s_waitcnt lgkmcnt(0)
	s_barrier
; __device__ __forceinline__ void p4_pass(const bf16_t* __restrict__ A, int K, const bf16_t* __restrict__ B, int rt, int ct, f32x16& c0, f32x16& c1, LAS char* lds, int tid, int r32, int hi, int wa, int wb) {
;     ...
;     for (int kt = 0; kt < nk; kt += 2) {
;         P4_STEP(kt, ga0, ha0, gb0, hb0, ga1, ha1, gb1, hb1);
;         P4_STEP(kt + 1, ga1, ha1, gb1, hb1, ga0, ha0, gb0, hb0);
;     }
	s_setprio 3
	ds_read_b128 v[106:109], v163 offset:55296
	ds_read_b128 v[110:113], v164 offset:36864
	ds_read_b128 v[114:117], v164 offset:36896
	ds_read_b128 v[118:121], v163 offset:55328
	v_mfma_f32_32x32x16_bf16 v[82:97], v[134:137], v[130:133], v[82:97]
	v_mfma_f32_32x32x16_bf16 v[66:81], v[138:141], v[130:133], v[66:81]
	s_waitcnt lgkmcnt(2)
	v_mfma_f32_32x32x16_bf16 v[82:97], v[106:109], v[110:113], v[82:97]
	ds_read_b128 v[106:109], v163 offset:59904
	ds_read_b128 v[130:133], v163 offset:59936
	s_waitcnt lgkmcnt(1)
	s_setprio 2
	v_mfma_f32_32x32x16_bf16 v[66:81], v[106:109], v[110:113], v[66:81]
	v_mfma_f32_32x32x16_bf16 v[82:97], v[118:121], v[114:117], v[82:97]
	s_waitcnt lgkmcnt(0)
	v_mfma_f32_32x32x16_bf16 v[66:81], v[130:133], v[114:117], v[66:81]
	ds_read_b128 v[106:109], v163 offset:55360
	ds_read_b128 v[110:113], v164 offset:36928
	ds_read_b128 v[114:117], v164 offset:36960
	ds_read_b128 v[118:121], v163 offset:55392
	s_waitcnt lgkmcnt(2)
	s_setprio 1
	v_mfma_f32_32x32x16_bf16 v[82:97], v[106:109], v[110:113], v[82:97]
	ds_read_b128 v[106:109], v163 offset:59968
	ds_read_b128 v[130:133], v163 offset:60000
	s_waitcnt lgkmcnt(1)
	v_mfma_f32_32x32x16_bf16 v[66:81], v[106:109], v[110:113], v[66:81]
	global_load_dwordx4 v[106:109], v[102:103], off offset:384
	v_mfma_f32_32x32x16_bf16 v[82:97], v[118:121], v[114:117], v[82:97]
	global_load_dwordx4 v[110:113], v[102:103], off offset:448
	global_load_dwordx4 v[118:121], v[104:105], off offset:384
	global_load_dwordx4 v[134:137], v[104:105], off offset:448
	s_waitcnt vmcnt(7)
	ds_write_b128 v162, v[122:125]
	s_waitcnt vmcnt(6)
	ds_write_b128 v162, v[126:129] offset:64
	s_waitcnt vmcnt(5)
	ds_write_b128 v162, v[142:145] offset:18432
	s_waitcnt vmcnt(4)
	ds_write_b128 v162, v[146:149] offset:18496
	s_waitcnt lgkmcnt(4)
	v_mfma_f32_32x32x16_bf16 v[66:81], v[130:133], v[114:117], v[66:81]
	s_setprio 0
	s_waitcnt lgkmcnt(0)
	s_barrier
	s_setprio 3
	ds_read_b128 v[114:117], v163 offset:18432
	ds_read_b128 v[122:125], v164
	ds_read_b128 v[126:129], v164 offset:32
	ds_read_b128 v[130:133], v163 offset:18464
	s_waitcnt lgkmcnt(2)
	v_mfma_f32_32x32x16_bf16 v[82:97], v[114:117], v[122:125], v[82:97]
	ds_read_b128 v[114:117], v163 offset:23040
	ds_read_b128 v[138:141], v163 offset:23072
	s_waitcnt lgkmcnt(1)
	v_mfma_f32_32x32x16_bf16 v[66:81], v[114:117], v[122:125], v[66:81]
	s_setprio 2
	v_mfma_f32_32x32x16_bf16 v[82:97], v[130:133], v[126:129], v[82:97]
	s_waitcnt lgkmcnt(0)
	v_mfma_f32_32x32x16_bf16 v[66:81], v[138:141], v[126:129], v[66:81]
	ds_read_b128 v[114:117], v163 offset:18496
	ds_read_b128 v[122:125], v164 offset:64
	ds_read_b128 v[126:129], v164 offset:96
	ds_read_b128 v[130:133], v163 offset:18528
	s_waitcnt lgkmcnt(2)
	s_setprio 1
	v_mfma_f32_32x32x16_bf16 v[82:97], v[114:117], v[122:125], v[82:97]
	ds_read_b128 v[114:117], v163 offset:23104
	ds_read_b128 v[138:141], v163 offset:23136
	s_waitcnt lgkmcnt(1)
	v_mfma_f32_32x32x16_bf16 v[66:81], v[114:117], v[122:125], v[66:81]
	global_load_dwordx4 v[114:117], v[102:103], off offset:512
	global_load_dwordx4 v[122:125], v[102:103], off offset:576
	global_load_dwordx4 v[142:145], v[104:105], off offset:512
	global_load_dwordx4 v[146:149], v[104:105], off offset:576
	s_waitcnt vmcnt(7)
	ds_write_b128 v162, v[106:109] offset:36864
	s_waitcnt vmcnt(6)
	ds_write_b128 v162, v[110:113] offset:36928
	s_waitcnt vmcnt(5)
	ds_write_b128 v162, v[118:121] offset:55296
	s_waitcnt vmcnt(4)
	ds_write_b128 v162, v[134:137] offset:55360
	v_mfma_f32_32x32x16_bf16 v[82:97], v[130:133], v[126:129], v[82:97]
	s_setprio 0
	s_waitcnt lgkmcnt(0)
	s_barrier
	s_setprio 3
	v_mfma_f32_32x32x16_bf16 v[66:81], v[138:141], v[126:129], v[66:81]
	ds_read_b128 v[106:109], v163 offset:55296
	ds_read_b128 v[110:113], v164 offset:36864
	ds_read_b128 v[118:121], v164 offset:36896
	ds_read_b128 v[126:129], v163 offset:55328
	s_waitcnt lgkmcnt(2)
	v_mfma_f32_32x32x16_bf16 v[82:97], v[106:109], v[110:113], v[82:97]
	ds_read_b128 v[106:109], v163 offset:59904
	ds_read_b128 v[130:133], v163 offset:59936
	s_waitcnt lgkmcnt(1)
	s_setprio 2
	v_mfma_f32_32x32x16_bf16 v[66:81], v[106:109], v[110:113], v[66:81]
	v_mfma_f32_32x32x16_bf16 v[82:97], v[126:129], v[118:121], v[82:97]
	s_waitcnt lgkmcnt(0)
	v_mfma_f32_32x32x16_bf16 v[66:81], v[130:133], v[118:121], v[66:81]
	ds_read_b128 v[106:109], v163 offset:55360
	ds_read_b128 v[110:113], v164 offset:36928
	ds_read_b128 v[118:121], v164 offset:36960
	ds_read_b128 v[126:129], v163 offset:55392
	s_waitcnt lgkmcnt(2)
	s_setprio 1
	v_mfma_f32_32x32x16_bf16 v[82:97], v[106:109], v[110:113], v[82:97]
	ds_read_b128 v[106:109], v163 offset:59968
	ds_read_b128 v[130:133], v163 offset:60000
	s_waitcnt lgkmcnt(1)
	v_mfma_f32_32x32x16_bf16 v[66:81], v[106:109], v[110:113], v[66:81]
	global_load_dwordx4 v[106:109], v[102:103], off offset:640
	v_mfma_f32_32x32x16_bf16 v[82:97], v[126:129], v[118:121], v[82:97]
	s_setprio 0
	global_load_dwordx4 v[110:113], v[102:103], off offset:704
	global_load_dwordx4 v[126:129], v[104:105], off offset:640
	global_load_dwordx4 v[134:137], v[104:105], off offset:704
	s_waitcnt vmcnt(7)
	ds_write_b128 v162, v[114:117]
	s_waitcnt vmcnt(6)
	ds_write_b128 v162, v[122:125] offset:64
	s_waitcnt vmcnt(5)
	ds_write_b128 v162, v[142:145] offset:18432
	s_waitcnt vmcnt(4)
	ds_write_b128 v162, v[146:149] offset:18496
	s_waitcnt lgkmcnt(0)
	s_barrier
; __device__ __forceinline__ void p4_pass(const bf16_t* __restrict__ A, int K, const bf16_t* __restrict__ B, int rt, int ct, f32x16& c0, f32x16& c1, LAS char* lds, int tid, int r32, int hi, int wa, int wb) {
;     ...
;     for (int kt = 0; kt < nk; kt += 2) {
;         P4_STEP(kt, ga0, ha0, gb0, hb0, ga1, ha1, gb1, hb1);
;         P4_STEP(kt + 1, ga1, ha1, gb1, hb1, ga0, ha0, gb0, hb0);
;     }
	s_setprio 3
	v_mfma_f32_32x32x16_bf16 v[66:81], v[130:133], v[118:121], v[66:81]
	ds_read_b128 v[114:117], v163 offset:18432
	ds_read_b128 v[118:121], v164
	ds_read_b128 v[122:125], v164 offset:32
	ds_read_b128 v[130:133], v163 offset:18464
	s_waitcnt lgkmcnt(2)
	v_mfma_f32_32x32x16_bf16 v[82:97], v[114:117], v[118:121], v[82:97]
	ds_read_b128 v[114:117], v163 offset:23040
	ds_read_b128 v[138:141], v163 offset:23072
	s_waitcnt lgkmcnt(1)
	s_setprio 2
	v_mfma_f32_32x32x16_bf16 v[66:81], v[114:117], v[118:121], v[66:81]
	v_mfma_f32_32x32x16_bf16 v[82:97], v[130:133], v[122:125], v[82:97]
	s_waitcnt lgkmcnt(0)
	v_mfma_f32_32x32x16_bf16 v[66:81], v[138:141], v[122:125], v[66:81]
	ds_read_b128 v[114:117], v163 offset:18496
	ds_read_b128 v[118:121], v164 offset:64
	ds_read_b128 v[122:125], v164 offset:96
	ds_read_b128 v[130:133], v163 offset:18528
	s_waitcnt lgkmcnt(2)
	s_setprio 1
	v_mfma_f32_32x32x16_bf16 v[82:97], v[114:117], v[118:121], v[82:97]
	ds_read_b128 v[114:117], v163 offset:23104
	ds_read_b128 v[138:141], v163 offset:23136
	s_waitcnt lgkmcnt(1)
	v_mfma_f32_32x32x16_bf16 v[66:81], v[114:117], v[118:121], v[66:81]
	global_load_dwordx4 v[114:117], v[102:103], off offset:768
	global_load_dwordx4 v[118:121], v[102:103], off offset:832
	global_load_dwordx4 v[142:145], v[104:105], off offset:768
	global_load_dwordx4 v[146:149], v[104:105], off offset:832
	s_waitcnt vmcnt(7)
	ds_write_b128 v162, v[106:109] offset:36864
	s_waitcnt vmcnt(6)
	ds_write_b128 v162, v[110:113] offset:36928
	s_waitcnt vmcnt(5)
	ds_write_b128 v162, v[126:129] offset:55296
	s_waitcnt vmcnt(4)
	ds_write_b128 v162, v[134:137] offset:55360
	v_mfma_f32_32x32x16_bf16 v[82:97], v[130:133], v[122:125], v[82:97]
	s_setprio 0
	s_waitcnt lgkmcnt(0)
	s_barrier
	s_setprio 3
	v_mfma_f32_32x32x16_bf16 v[66:81], v[138:141], v[122:125], v[66:81]
	ds_read_b128 v[106:109], v163 offset:55296
	ds_read_b128 v[110:113], v164 offset:36864
	ds_read_b128 v[122:125], v164 offset:36896
	ds_read_b128 v[126:129], v163 offset:55328
	s_waitcnt lgkmcnt(2)
	v_mfma_f32_32x32x16_bf16 v[82:97], v[106:109], v[110:113], v[82:97]
	ds_read_b128 v[106:109], v163 offset:59904
	ds_read_b128 v[130:133], v163 offset:59936
	s_waitcnt lgkmcnt(1)
	s_setprio 2
	v_mfma_f32_32x32x16_bf16 v[66:81], v[106:109], v[110:113], v[66:81]
	v_mfma_f32_32x32x16_bf16 v[82:97], v[126:129], v[122:125], v[82:97]
	s_waitcnt lgkmcnt(0)
	v_mfma_f32_32x32x16_bf16 v[66:81], v[130:133], v[122:125], v[66:81]
	ds_read_b128 v[106:109], v163 offset:55360
	ds_read_b128 v[110:113], v164 offset:36928
	ds_read_b128 v[122:125], v164 offset:36960
	ds_read_b128 v[126:129], v163 offset:55392
	s_waitcnt lgkmcnt(2)
	s_setprio 1
	v_mfma_f32_32x32x16_bf16 v[82:97], v[106:109], v[110:113], v[82:97]
	ds_read_b128 v[106:109], v163 offset:59968
	ds_read_b128 v[130:133], v163 offset:60000
	s_waitcnt lgkmcnt(1)
	v_mfma_f32_32x32x16_bf16 v[66:81], v[106:109], v[110:113], v[66:81]
	global_load_dwordx4 v[106:109], v[102:103], off offset:896
	v_mfma_f32_32x32x16_bf16 v[82:97], v[126:129], v[122:125], v[82:97]
	s_setprio 0
	global_load_dwordx4 v[110:113], v[102:103], off offset:960
	global_load_dwordx4 v[126:129], v[104:105], off offset:896
	s_nop 0
	global_load_dwordx4 v[102:105], v[104:105], off offset:960
	s_waitcnt vmcnt(7)
	ds_write_b128 v162, v[114:117]
	s_waitcnt vmcnt(6)
	ds_write_b128 v162, v[118:121] offset:64
	s_waitcnt vmcnt(5)
	ds_write_b128 v162, v[142:145] offset:18432
	s_waitcnt vmcnt(4)
	ds_write_b128 v162, v[146:149] offset:18496
	s_waitcnt lgkmcnt(0)
	s_barrier
	s_setprio 3
	v_mfma_f32_32x32x16_bf16 v[66:81], v[130:133], v[122:125], v[66:81]
	ds_read_b128 v[114:117], v163 offset:18432
	ds_read_b128 v[118:121], v164
	ds_read_b128 v[122:125], v164 offset:32
	ds_read_b128 v[130:133], v163 offset:18464
	s_waitcnt lgkmcnt(2)
	v_mfma_f32_32x32x16_bf16 v[82:97], v[114:117], v[118:121], v[82:97]
	ds_read_b128 v[114:117], v163 offset:23040
	ds_read_b128 v[134:137], v163 offset:23072
	s_waitcnt lgkmcnt(1)
	s_setprio 2
	v_mfma_f32_32x32x16_bf16 v[66:81], v[114:117], v[118:121], v[66:81]
	v_mfma_f32_32x32x16_bf16 v[82:97], v[130:133], v[122:125], v[82:97]
	s_waitcnt lgkmcnt(0)
	s_setprio 1
	v_mfma_f32_32x32x16_bf16 v[66:81], v[134:137], v[122:125], v[66:81]
	ds_read_b128 v[114:117], v163 offset:18496
	ds_read_b128 v[118:121], v164 offset:64
	ds_read_b128 v[122:125], v164 offset:96
	ds_read_b128 v[130:133], v163 offset:18528
	s_waitcnt lgkmcnt(2)
	v_mfma_f32_32x32x16_bf16 v[82:97], v[114:117], v[118:121], v[82:97]
	ds_read_b128 v[114:117], v163 offset:23104
	ds_read_b128 v[134:137], v163 offset:23136
	s_waitcnt vmcnt(3)
	ds_write_b128 v162, v[106:109] offset:36864
	s_waitcnt vmcnt(2)
	ds_write_b128 v162, v[110:113] offset:36928
	s_waitcnt vmcnt(1)
	ds_write_b128 v162, v[126:129] offset:55296
	s_waitcnt vmcnt(0)
	ds_write_b128 v162, v[102:105] offset:55360
	s_waitcnt lgkmcnt(5)
	v_mfma_f32_32x32x16_bf16 v[66:81], v[114:117], v[118:121], v[66:81]
	s_setprio 0
	s_waitcnt lgkmcnt(0)
	s_barrier
	s_setprio 3
	ds_read_b128 v[102:105], v163 offset:55296
	ds_read_b128 v[106:109], v164 offset:36864
	ds_read_b128 v[110:113], v164 offset:36896
	ds_read_b128 v[114:117], v163 offset:55328
	v_mfma_f32_32x32x16_bf16 v[82:97], v[130:133], v[122:125], v[82:97]
	v_mfma_f32_32x32x16_bf16 v[66:81], v[134:137], v[122:125], v[66:81]
	s_waitcnt lgkmcnt(2)
	s_setprio 2
	v_mfma_f32_32x32x16_bf16 v[82:97], v[102:105], v[106:109], v[82:97]
	ds_read_b128 v[102:105], v163 offset:59904
	ds_read_b128 v[118:121], v163 offset:59936
	s_waitcnt lgkmcnt(1)
	v_mfma_f32_32x32x16_bf16 v[66:81], v[102:105], v[106:109], v[66:81]
	s_setprio 1
	v_mfma_f32_32x32x16_bf16 v[82:97], v[114:117], v[110:113], v[82:97]
	s_waitcnt lgkmcnt(0)
	v_mfma_f32_32x32x16_bf16 v[66:81], v[118:121], v[110:113], v[66:81]
	ds_read_b128 v[98:101], v163 offset:55360
	ds_read_b128 v[102:105], v164 offset:36928
	ds_read_b128 v[106:109], v163 offset:59968
	ds_read_b128 v[110:113], v164 offset:36960
	ds_read_b128 v[114:117], v163 offset:55392
	s_waitcnt lgkmcnt(3)
	v_mfma_f32_32x32x16_bf16 v[82:97], v[98:101], v[102:105], v[82:97]
	s_setprio 0
	ds_read_b128 v[98:101], v163 offset:60000
	s_waitcnt lgkmcnt(0)
	s_barrier
; #define LAS __attribute__((address_space(3)))
; __device__ __forceinline__ float sigm_f(float v) { return fast_rcp(1.f + fast_exp2(-v * LOG2E)); }
; __device__ __forceinline__ void p4_pass(const bf16_t* __restrict__ A, int K, const bf16_t* __restrict__ B, int rt, int ct, f32x16& c0, f32x16& c1, LAS char* lds, int tid, int r32, int hi, int wa, int wb) {
;     const bf16_t* asrc = A + (size_t)(rt * 128 + (tid >> 2)) * K + (tid & 3) * 8;
;     const bf16_t* bsrc = B + (size_t)(ct * 128 + (tid >> 2)) * K + (tid & 3) * 8;
;     const int sdst = (tid >> 2) * P4_PITCH + (tid & 3) * 16;
;     const int xoff = (wa * 32 + r32) * P4_PITCH + hi * 16, woff = P4_OPB + (wb * 64 + r32) * P4_PITCH + hi * 16;
;     const int nk = K >> 6;
;     u32x4 ga0 = *(const u32x4*)asrc, ha0 = *(const u32x4*)(asrc + 32), gb0 = *(const u32x4*)bsrc, hb0 = *(const u32x4*)(bsrc + 32), ga1, ha1, gb1, hb1;
;     *(LAS u32x4*)(lds + sdst) = ga0; *(LAS u32x4*)(lds + sdst + 64) = ha0; *(LAS u32x4*)(lds + P4_OPB + sdst) = gb0; *(LAS u32x4*)(lds + P4_OPB + sdst + 64) = hb0;
;     ga1 = *(const u32x4*)(asrc + 64); ha1 = *(const u32x4*)(asrc + 96); gb1 = *(const u32x4*)(bsrc + 64); hb1 = *(const u32x4*)(bsrc + 96);
;     __syncthreads();
;     c0 = (f32x16){}; c1 = (f32x16){};
;     ...
;     for (int kt = 0; kt < nk; kt += 2) {
;         P4_STEP(kt, ga0, ha0, gb0, hb0, ga1, ha1, gb1, hb1);
;         P4_STEP(kt + 1, ga1, ha1, gb1, hb1, ga0, ha0, gb0, hb0);
;     }
; __device__ __forceinline__ void p4_unit(int rt, int ct, const bf16_t* H, const bf16_t* YA, const bf16_t* YM, const bf16_t* Wga, const bf16_t* Wgm, const bf16_t* Wa, const bf16_t* Wb, bf16_t* MERGED, LAS char* lds) {
;     ...
;     for (int r = 0; r < 16; ++r) { g0[r] = sigm_f(g0[r]); g1[r] = sigm_f(g1[r]); m0[r] = sigm_f(m0[r]); m1[r] = sigm_f(m1[r]); }
;     p4_pass(YA, 512, Wa, rt, ct, c0, c1, lds, tid, r32, hi, wa, wb);
;     g0 *= c0; g1 *= c1;
;     p4_pass(YM, 1024, Wb, rt, ct, c0, c1, lds, tid, r32, hi, wa, wb);
	global_load_dwordx4 v[118:121], v[158:159], off
	global_load_dwordx4 v[122:125], v[158:159], off offset:64
	global_load_dwordx4 v[126:129], v[160:161], off
	v_mfma_f32_32x32x16_bf16 v[66:81], v[106:109], v[102:105], v[66:81]
	global_load_dwordx4 v[102:105], v[160:161], off offset:64
	global_load_dwordx4 v[146:149], v[158:159], off offset:128
	global_load_dwordx4 v[150:153], v[158:159], off offset:192
	global_load_dwordx4 v[154:157], v[160:161], off offset:128
	global_load_dwordx4 v[168:171], v[160:161], off offset:192
	s_waitcnt vmcnt(7)
	ds_write_b128 v162, v[118:121]
	s_waitcnt vmcnt(6)
	ds_write_b128 v162, v[122:125] offset:64
	s_waitcnt vmcnt(5)
	ds_write_b128 v162, v[126:129] offset:18432
	s_waitcnt vmcnt(4)
	ds_write_b128 v162, v[102:105] offset:18496
	v_mfma_f32_32x32x16_bf16 v[66:81], v[98:101], v[110:113], v[66:81]
	s_waitcnt lgkmcnt(0)
	s_barrier
	s_setprio 3
	ds_read_b128 v[98:101], v163 offset:18432
	ds_read_b128 v[102:105], v164
	ds_read_b128 v[130:133], v164 offset:32
	ds_read_b128 v[134:137], v163 offset:18464
	v_mfma_f32_32x32x16_bf16 v[82:97], v[114:117], v[110:113], v[82:97]
	s_waitcnt lgkmcnt(2)
	v_mfma_f32_32x32x16_bf16 v[114:129], v[98:101], v[102:105], 0
	ds_read_b128 v[98:101], v163 offset:23040
	ds_read_b128 v[138:141], v163 offset:23072
	s_waitcnt lgkmcnt(1)
	s_setprio 2
	v_mfma_f32_32x32x16_bf16 v[98:113], v[98:101], v[102:105], 0
	v_mfma_f32_32x32x16_bf16 v[114:129], v[134:137], v[130:133], v[114:129]
	s_waitcnt lgkmcnt(0)
	s_setprio 1
	v_mfma_f32_32x32x16_bf16 v[98:113], v[138:141], v[130:133], v[98:113]
	ds_read_b128 v[130:133], v163 offset:18496
	ds_read_b128 v[134:137], v164 offset:64
	ds_read_b128 v[172:175], v164 offset:96
	ds_read_b128 v[188:191], v163 offset:18528
	s_waitcnt lgkmcnt(2)
	v_mfma_f32_32x32x16_bf16 v[114:129], v[130:133], v[134:137], v[114:129]
	ds_read_b128 v[130:133], v163 offset:23104
	ds_read_b128 v[192:195], v163 offset:23136
	s_waitcnt lgkmcnt(1)
	v_mfma_f32_32x32x16_bf16 v[98:113], v[130:133], v[134:137], v[98:113]
	s_setprio 0
	global_load_dwordx4 v[130:133], v[158:159], off offset:256
	global_load_dwordx4 v[134:137], v[158:159], off offset:320
	global_load_dwordx4 v[138:141], v[160:161], off offset:256
	global_load_dwordx4 v[142:145], v[160:161], off offset:320
	s_waitcnt vmcnt(7)
	ds_write_b128 v162, v[146:149] offset:36864
	s_waitcnt vmcnt(6)
	ds_write_b128 v162, v[150:153] offset:36928
	s_waitcnt vmcnt(5)
	ds_write_b128 v162, v[154:157] offset:55296
	s_waitcnt vmcnt(4)
	ds_write_b128 v162, v[168:171] offset:55360
	s_waitcnt lgkmcnt(0)
	s_barrier
	s_setprio 3
	ds_read_b128 v[146:149], v163 offset:55296
	ds_read_b128 v[150:153], v164 offset:36864
	ds_read_b128 v[154:157], v164 offset:36896
	ds_read_b128 v[168:171], v163 offset:55328
	v_mfma_f32_32x32x16_bf16 v[114:129], v[188:191], v[172:175], v[114:129]
	v_mfma_f32_32x32x16_bf16 v[98:113], v[192:195], v[172:175], v[98:113]
	s_waitcnt lgkmcnt(2)
	v_mfma_f32_32x32x16_bf16 v[114:129], v[146:149], v[150:153], v[114:129]
	ds_read_b128 v[146:149], v163 offset:59904
	ds_read_b128 v[172:175], v163 offset:59936
	s_waitcnt lgkmcnt(1)
	s_setprio 2
	v_mfma_f32_32x32x16_bf16 v[98:113], v[146:149], v[150:153], v[98:113]
	v_mfma_f32_32x32x16_bf16 v[114:129], v[168:171], v[154:157], v[114:129]
	s_waitcnt lgkmcnt(0)
	v_mfma_f32_32x32x16_bf16 v[98:113], v[172:175], v[154:157], v[98:113]
	ds_read_b128 v[154:157], v163 offset:55360
	ds_read_b128 v[168:171], v164 offset:36928
	ds_read_b128 v[146:149], v164 offset:36960
	ds_read_b128 v[150:153], v163 offset:55392
	s_waitcnt lgkmcnt(2)
	s_setprio 1
	v_mfma_f32_32x32x16_bf16 v[114:129], v[154:157], v[168:171], v[114:129]
	ds_read_b128 v[172:175], v163 offset:59968
	ds_read_b128 v[154:157], v163 offset:60000
	s_waitcnt lgkmcnt(1)
	v_mfma_f32_32x32x16_bf16 v[98:113], v[172:175], v[168:171], v[98:113]
	global_load_dwordx4 v[168:171], v[158:159], off offset:384
	v_mfma_f32_32x32x16_bf16 v[114:129], v[150:153], v[146:149], v[114:129]
	global_load_dwordx4 v[150:153], v[158:159], off offset:448
	global_load_dwordx4 v[172:175], v[160:161], off offset:384
	global_load_dwordx4 v[188:191], v[160:161], off offset:448
	s_waitcnt vmcnt(7)
	ds_write_b128 v162, v[130:133]
	s_waitcnt vmcnt(6)
	ds_write_b128 v162, v[134:137] offset:64
	s_waitcnt vmcnt(5)
	ds_write_b128 v162, v[138:141] offset:18432
	s_waitcnt vmcnt(4)
	ds_write_b128 v162, v[142:145] offset:18496
	s_waitcnt lgkmcnt(4)
	v_mfma_f32_32x32x16_bf16 v[98:113], v[154:157], v[146:149], v[98:113]
	s_setprio 0
	s_waitcnt lgkmcnt(0)
	s_barrier
	s_setprio 3
	ds_read_b128 v[130:133], v163 offset:18432
	ds_read_b128 v[134:137], v164
	ds_read_b128 v[138:141], v164 offset:32
	ds_read_b128 v[142:145], v163 offset:18464
	s_waitcnt lgkmcnt(2)
	v_mfma_f32_32x32x16_bf16 v[114:129], v[130:133], v[134:137], v[114:129]
	ds_read_b128 v[130:133], v163 offset:23040
	ds_read_b128 v[146:149], v163 offset:23072
	s_waitcnt lgkmcnt(1)
	v_mfma_f32_32x32x16_bf16 v[98:113], v[130:133], v[134:137], v[98:113]
	v_or_b32_e32 v130, s65, v166
	v_ashrrev_i32_e32 v131, 31, v130
	v_lshlrev_b64 v[130:131], 11, v[130:131]
	v_lshl_add_u64 v[130:131], s[4:5], 0, v[130:131]
	v_lshl_add_u64 v[130:131], v[130:131], 0, s[42:43]
	v_lshl_add_u64 v[130:131], s[22:23], 1, v[130:131]
	v_lshl_add_u64 v[130:131], v[130:131], 0, v[0:1]
	s_setprio 2
	v_mfma_f32_32x32x16_bf16 v[114:129], v[142:145], v[138:141], v[114:129]
	v_mul_f32_e32 v0, 0xbfb8aa3b, v50
	v_exp_f32_e32 v0, v0
	s_nop 0
	v_add_f32_e32 v0, 1.0, v0
	s_waitcnt lgkmcnt(0)
	v_mfma_f32_32x32x16_bf16 v[98:113], v[146:149], v[138:141], v[98:113]
	ds_read_b128 v[132:135], v163 offset:18496
	ds_read_b128 v[136:139], v164 offset:64
	ds_read_b128 v[140:143], v164 offset:96
	ds_read_b128 v[144:147], v163 offset:18528
	s_waitcnt lgkmcnt(2)
	s_setprio 1
	v_mfma_f32_32x32x16_bf16 v[114:129], v[132:135], v[136:139], v[114:129]
	ds_read_b128 v[132:135], v163 offset:23104
	ds_read_b128 v[154:157], v163 offset:23136
	s_waitcnt lgkmcnt(1)
	v_mfma_f32_32x32x16_bf16 v[98:113], v[132:135], v[136:139], v[98:113]
	global_load_dwordx4 v[50:53], v[158:159], off offset:512
	global_load_dwordx4 v[132:135], v[158:159], off offset:576
	global_load_dwordx4 v[136:139], v[160:161], off offset:512
	global_load_dwordx4 v[192:195], v[160:161], off offset:576
	s_waitcnt vmcnt(7)
	ds_write_b128 v162, v[168:171] offset:36864
	s_waitcnt vmcnt(6)
	ds_write_b128 v162, v[150:153] offset:36928
	s_waitcnt vmcnt(5)
	ds_write_b128 v162, v[172:175] offset:55296
	s_waitcnt vmcnt(4)
	ds_write_b128 v162, v[188:191] offset:55360
	v_mfma_f32_32x32x16_bf16 v[114:129], v[144:147], v[140:143], v[114:129]
	s_setprio 0
	s_waitcnt lgkmcnt(0)
	s_barrier
; __device__ __forceinline__ float sigm_f(float v) { return fast_rcp(1.f + fast_exp2(-v * LOG2E)); }
; __device__ __forceinline__ void p4_pass(const bf16_t* __restrict__ A, int K, const bf16_t* __restrict__ B, int rt, int ct, f32x16& c0, f32x16& c1, LAS char* lds, int tid, int r32, int hi, int wa, int wb) {
;     ...
;     for (int kt = 0; kt < nk; kt += 2) {
;         P4_STEP(kt, ga0, ha0, gb0, hb0, ga1, ha1, gb1, hb1);
;         P4_STEP(kt + 1, ga1, ha1, gb1, hb1, ga0, ha0, gb0, hb0);
;     }
; __device__ __forceinline__ void p4_unit(int rt, int ct, const bf16_t* H, const bf16_t* YA, const bf16_t* YM, const bf16_t* Wga, const bf16_t* Wgm, const bf16_t* Wa, const bf16_t* Wb, bf16_t* MERGED, LAS char* lds) {
;     ...
;     for (int r = 0; r < 16; ++r) { g0[r] = sigm_f(g0[r]); g1[r] = sigm_f(g1[r]); m0[r] = sigm_f(m0[r]); m1[r] = sigm_f(m1[r]); }
	s_setprio 3
	v_mul_f32_e32 v170, 0xbfb8aa3b, v57
	v_mul_f32_e32 v171, 0xbfb8aa3b, v58
	v_mul_f32_e32 v172, 0xbfb8aa3b, v59
	v_mul_f32_e32 v173, 0xbfb8aa3b, v60
	v_mfma_f32_32x32x16_bf16 v[98:113], v[154:157], v[140:143], v[98:113]
	ds_read_b128 v[140:143], v163 offset:55296
	ds_read_b128 v[144:147], v164 offset:36864
	ds_read_b128 v[148:151], v164 offset:36896
	ds_read_b128 v[152:155], v163 offset:55328
	v_mul_f32_e32 v156, 0xbfb8aa3b, v55
	v_mul_f32_e32 v157, 0xbfb8aa3b, v56
	v_mul_f32_e32 v174, 0xbfb8aa3b, v61
	v_mul_f32_e32 v175, 0xbfb8aa3b, v34
	v_mul_f32_e32 v188, 0xbfb8aa3b, v35
	v_mul_f32_e32 v189, 0xbfb8aa3b, v36
	s_waitcnt lgkmcnt(2)
	v_mfma_f32_32x32x16_bf16 v[114:129], v[140:143], v[144:147], v[114:129]
	ds_read_b128 v[140:143], v163 offset:59904
	ds_read_b128 v[166:169], v163 offset:59936
	v_mul_f32_e32 v190, 0xbfb8aa3b, v49
	v_mul_f32_e32 v191, 0xbfb8aa3b, v21
	v_exp_f32_e32 v156, v156
	v_exp_f32_e32 v157, v157
	v_add_f32_e32 v156, 1.0, v156
	s_waitcnt lgkmcnt(1)
	s_setprio 2
	v_mfma_f32_32x32x16_bf16 v[98:113], v[140:143], v[144:147], v[98:113]
	v_add_f32_e32 v157, 1.0, v157
	v_mfma_f32_32x32x16_bf16 v[114:129], v[152:155], v[148:151], v[114:129]
	v_mul_f32_e32 v152, 0xbfb8aa3b, v62
	v_mul_f32_e32 v153, 0xbfb8aa3b, v63
	v_mul_f32_e32 v154, 0xbfb8aa3b, v64
	v_mul_f32_e32 v155, 0xbfb8aa3b, v65
	ds_read_b128 v[54:57], v163 offset:55360
	ds_read_b128 v[58:61], v164 offset:36928
	ds_read_b128 v[62:65], v164 offset:36960
	ds_read_b128 v[140:143], v163 offset:55392
	v_exp_f32_e32 v152, v152
	v_exp_f32_e32 v153, v153
	s_waitcnt lgkmcnt(4)
	s_setprio 1
	v_mfma_f32_32x32x16_bf16 v[98:113], v[166:169], v[148:151], v[98:113]
	v_mul_f32_e32 v148, 0xbfb8aa3b, v37
	v_mul_f32_e32 v149, 0xbfb8aa3b, v38
	v_mul_f32_e32 v150, 0xbfb8aa3b, v39
	v_mul_f32_e32 v151, 0xbfb8aa3b, v40
	v_mul_f32_e32 v166, 0xbfb8aa3b, v41
	v_mul_f32_e32 v167, 0xbfb8aa3b, v42
	v_mul_f32_e32 v168, 0xbfb8aa3b, v47
	s_waitcnt lgkmcnt(2)
	v_mfma_f32_32x32x16_bf16 v[114:129], v[54:57], v[58:61], v[114:129]
	ds_read_b128 v[54:57], v163 offset:59968
	ds_read_b128 v[144:147], v163 offset:60000
	global_load_dwordx4 v[34:37], v[158:159], off offset:640
	v_mul_f32_e32 v169, 0xbfb8aa3b, v48
	v_exp_f32_e32 v148, v148
	v_exp_f32_e32 v149, v149
	v_exp_f32_e32 v150, v150
	v_exp_f32_e32 v151, v151
	s_waitcnt lgkmcnt(1)
	v_mfma_f32_32x32x16_bf16 v[98:113], v[54:57], v[58:61], v[98:113]
	s_setprio 0
	global_load_dwordx4 v[38:41], v[158:159], off offset:704
	global_load_dwordx4 v[54:57], v[160:161], off offset:640
	global_load_dwordx4 v[58:61], v[160:161], off offset:704
	s_waitcnt vmcnt(7)
	ds_write_b128 v162, v[50:53]
	s_waitcnt vmcnt(6)
	ds_write_b128 v162, v[132:135] offset:64
	s_waitcnt vmcnt(5)
	ds_write_b128 v162, v[136:139] offset:18432
	s_waitcnt vmcnt(4)
	ds_write_b128 v162, v[192:195] offset:18496
	s_waitcnt lgkmcnt(0)
	s_barrier
	s_setprio 3
	v_mul_f32_e32 v192, 0xbfb8aa3b, v22
	v_mul_f32_e32 v193, 0xbfb8aa3b, v23
	v_mfma_f32_32x32x16_bf16 v[114:129], v[140:143], v[62:65], v[114:129]
	v_mul_f32_e32 v194, 0xbfb8aa3b, v8
	v_exp_f32_e32 v166, v166
	v_exp_f32_e32 v167, v167
	v_add_f32_e32 v148, 1.0, v148
	v_exp_f32_e32 v168, v168
	v_exp_f32_e32 v169, v169
	v_add_f32_e32 v149, 1.0, v149
	v_mfma_f32_32x32x16_bf16 v[98:113], v[144:147], v[62:65], v[98:113]
	ds_read_b128 v[50:53], v163 offset:18432
	ds_read_b128 v[62:65], v164
	ds_read_b128 v[132:135], v164 offset:32
	ds_read_b128 v[136:139], v163 offset:18464
	v_mul_f32_e32 v144, 0xbfb8aa3b, v43
	v_mul_f32_e32 v145, 0xbfb8aa3b, v44
	v_mul_f32_e32 v146, 0xbfb8aa3b, v45
	v_mul_f32_e32 v147, 0xbfb8aa3b, v46
	v_exp_f32_e32 v144, v144
	v_exp_f32_e32 v145, v145
	s_waitcnt lgkmcnt(2)
	v_mfma_f32_32x32x16_bf16 v[114:129], v[50:53], v[62:65], v[114:129]
	ds_read_b128 v[50:53], v163 offset:23040
	ds_read_b128 v[140:143], v163 offset:23072
	v_exp_f32_e32 v146, v146
	v_exp_f32_e32 v147, v147
	v_add_f32_e32 v150, 1.0, v150
	v_add_f32_e32 v151, 1.0, v151
	v_add_f32_e32 v166, 1.0, v166
	v_add_f32_e32 v167, 1.0, v167
	s_waitcnt lgkmcnt(1)
	s_setprio 2
	v_mfma_f32_32x32x16_bf16 v[98:113], v[50:53], v[62:65], v[98:113]
	v_add_f32_e32 v144, 1.0, v144
	v_add_f32_e32 v145, 1.0, v145
	v_add_f32_e32 v146, 1.0, v146
	v_exp_f32_e32 v154, v154
	v_exp_f32_e32 v155, v155
	v_add_f32_e32 v147, 1.0, v147
	v_add_f32_e32 v168, 1.0, v168
	v_mfma_f32_32x32x16_bf16 v[114:129], v[136:139], v[132:135], v[114:129]
	v_mul_f32_e32 v137, 0xbfb8aa3b, v18
	v_mul_f32_e32 v138, 0xbfb8aa3b, v19
	v_mul_f32_e32 v139, 0xbfb8aa3b, v20
	ds_read_b128 v[18:21], v163 offset:18496
	ds_read_b128 v[42:45], v164 offset:64
	ds_read_b128 v[46:49], v164 offset:96
	ds_read_b128 v[50:53], v163 offset:18528
	v_mul_f32_e32 v136, 0xbfb8aa3b, v33
	v_exp_f32_e32 v137, v137
	v_exp_f32_e32 v138, v138
	s_waitcnt lgkmcnt(4)
	v_mfma_f32_32x32x16_bf16 v[98:113], v[140:143], v[132:135], v[98:113]
	v_mul_f32_e32 v140, 0xbfb8aa3b, v24
	v_mul_f32_e32 v141, 0xbfb8aa3b, v25
	v_mul_f32_e32 v142, 0xbfb8aa3b, v26
	v_mul_f32_e32 v143, 0xbfb8aa3b, v7
	v_exp_f32_e32 v139, v139
	v_exp_f32_e32 v140, v140
	v_exp_f32_e32 v141, v141
	s_waitcnt lgkmcnt(2)
	s_setprio 1
	v_mfma_f32_32x32x16_bf16 v[114:129], v[18:21], v[42:45], v[114:129]
	ds_read_b128 v[18:21], v163 offset:23104
	ds_read_b128 v[62:65], v163 offset:23136
	v_exp_f32_e32 v142, v142
	v_exp_f32_e32 v143, v143
	v_add_f32_e32 v195, 1.0, v138
	v_exp_f32_e32 v136, v136
	v_add_f32_e32 v206, 1.0, v142
	v_add_f32_e32 v219, 1.0, v143
	s_waitcnt lgkmcnt(1)
	v_mfma_f32_32x32x16_bf16 v[98:113], v[18:21], v[42:45], v[98:113]
	global_load_dwordx4 v[18:21], v[158:159], off offset:768
	global_load_dwordx4 v[22:25], v[158:159], off offset:832
	global_load_dwordx4 v[42:45], v[160:161], off offset:768
	global_load_dwordx4 v[132:135], v[160:161], off offset:832
	s_waitcnt vmcnt(7)
	ds_write_b128 v162, v[34:37] offset:36864
	s_waitcnt vmcnt(6)
	ds_write_b128 v162, v[38:41] offset:36928
	s_waitcnt vmcnt(5)
	ds_write_b128 v162, v[54:57] offset:55296
	s_waitcnt vmcnt(4)
	ds_write_b128 v162, v[58:61] offset:55360
	v_mfma_f32_32x32x16_bf16 v[114:129], v[50:53], v[46:49], v[114:129]
	s_setprio 0
	s_waitcnt lgkmcnt(0)
	s_barrier
; __device__ __forceinline__ float sigm_f(float v) { return fast_rcp(1.f + fast_exp2(-v * LOG2E)); }
; __device__ __forceinline__ void p4_pass(const bf16_t* __restrict__ A, int K, const bf16_t* __restrict__ B, int rt, int ct, f32x16& c0, f32x16& c1, LAS char* lds, int tid, int r32, int hi, int wa, int wb) {
;     ...
;     for (int kt = 0; kt < nk; kt += 2) {
;         P4_STEP(kt, ga0, ha0, gb0, hb0, ga1, ha1, gb1, hb1);
;         P4_STEP(kt + 1, ga1, ha1, gb1, hb1, ga0, ha0, gb0, hb0);
;     }
; __device__ __forceinline__ void p4_unit(int rt, int ct, const bf16_t* H, const bf16_t* YA, const bf16_t* YM, const bf16_t* Wga, const bf16_t* Wgm, const bf16_t* Wa, const bf16_t* Wb, bf16_t* MERGED, LAS char* lds) {
;     ...
;     for (int r = 0; r < 16; ++r) { g0[r] = sigm_f(g0[r]); g1[r] = sigm_f(g1[r]); m0[r] = sigm_f(m0[r]); m1[r] = sigm_f(m1[r]); }
	s_setprio 3
	v_mul_f32_e32 v58, 0xbfb8aa3b, v27
	v_mul_f32_e32 v59, 0xbfb8aa3b, v28
	v_mul_f32_e32 v60, 0xbfb8aa3b, v29
	v_mul_f32_e32 v61, 0xbfb8aa3b, v30
	v_mfma_f32_32x32x16_bf16 v[98:113], v[62:65], v[46:49], v[98:113]
	ds_read_b128 v[34:37], v163 offset:55296
	ds_read_b128 v[38:41], v164 offset:36864
	ds_read_b128 v[46:49], v164 offset:36896
	ds_read_b128 v[50:53], v163 offset:55328
	v_mul_f32_e32 v62, 0xbfb8aa3b, v31
	v_mul_f32_e32 v63, 0xbfb8aa3b, v32
	v_mul_f32_e32 v65, 0xbfb8aa3b, v6
	v_mul_f32_e32 v64, 0xbfb8aa3b, v17
	v_exp_f32_e32 v58, v58
	v_exp_f32_e32 v59, v59
	s_waitcnt lgkmcnt(2)
	v_mfma_f32_32x32x16_bf16 v[114:129], v[34:37], v[38:41], v[114:129]
	ds_read_b128 v[34:37], v163 offset:59904
	ds_read_b128 v[54:57], v163 offset:59936
	v_exp_f32_e32 v60, v60
	v_exp_f32_e32 v62, v62
	v_exp_f32_e32 v63, v63
	v_exp_f32_e32 v64, v64
	v_exp_f32_e32 v65, v65
	v_add_f32_e32 v207, 1.0, v58
	s_waitcnt lgkmcnt(1)
	s_setprio 2
	v_mfma_f32_32x32x16_bf16 v[98:113], v[34:37], v[38:41], v[98:113]
	v_add_f32_e32 v208, 1.0, v59
	v_add_f32_e32 v209, 1.0, v60
	v_exp_f32_e32 v61, v61
	v_add_f32_e32 v211, 1.0, v62
	v_add_f32_e32 v212, 1.0, v63
	v_add_f32_e32 v213, 1.0, v64
	v_add_f32_e32 v218, 1.0, v65
	v_mfma_f32_32x32x16_bf16 v[114:129], v[50:53], v[46:49], v[114:129]
	v_mul_f32_e32 v50, 0xbfb8aa3b, v2
	v_mul_f32_e32 v51, 0xbfb8aa3b, v3
	v_mul_f32_e32 v52, 0xbfb8aa3b, v4
	v_mul_f32_e32 v53, 0xbfb8aa3b, v5
	ds_read_b128 v[2:5], v163 offset:55360
	ds_read_b128 v[26:29], v164 offset:36928
	ds_read_b128 v[30:33], v164 offset:36960
	ds_read_b128 v[34:37], v163 offset:55392
	v_exp_f32_e32 v50, v50
	v_exp_f32_e32 v51, v51
	s_waitcnt lgkmcnt(4)
	v_mfma_f32_32x32x16_bf16 v[98:113], v[54:57], v[46:49], v[98:113]
	v_mul_f32_e32 v46, 0xbfb8aa3b, v9
	v_mul_f32_e32 v47, 0xbfb8aa3b, v10
	v_mul_f32_e32 v48, 0xbfb8aa3b, v11
	v_mul_f32_e32 v49, 0xbfb8aa3b, v12
	v_mul_f32_e32 v54, 0xbfb8aa3b, v13
	v_mul_f32_e32 v55, 0xbfb8aa3b, v14
	v_mul_f32_e32 v56, 0xbfb8aa3b, v15
	s_waitcnt lgkmcnt(2)
	s_setprio 1
	v_mfma_f32_32x32x16_bf16 v[114:129], v[2:5], v[26:29], v[114:129]
	ds_read_b128 v[2:5], v163 offset:59968
	ds_read_b128 v[38:41], v163 offset:60000
	v_mul_f32_e32 v57, 0xbfb8aa3b, v16
	v_exp_f32_e32 v52, v52
	v_exp_f32_e32 v53, v53
	v_exp_f32_e32 v46, v46
	v_exp_f32_e32 v47, v47
	v_exp_f32_e32 v48, v48
	s_waitcnt lgkmcnt(1)
	v_mfma_f32_32x32x16_bf16 v[98:113], v[2:5], v[26:29], v[98:113]
	global_load_dwordx4 v[2:5], v[158:159], off offset:896
	global_load_dwordx4 v[6:9], v[158:159], off offset:960
	global_load_dwordx4 v[10:13], v[160:161], off offset:896
	global_load_dwordx4 v[26:29], v[160:161], off offset:960
	s_waitcnt vmcnt(7)
	ds_write_b128 v162, v[18:21]
	s_waitcnt vmcnt(6)
	ds_write_b128 v162, v[22:25] offset:64
	s_waitcnt vmcnt(5)
	ds_write_b128 v162, v[42:45] offset:18432
	s_waitcnt vmcnt(4)
	ds_write_b128 v162, v[132:135] offset:18496
	v_mfma_f32_32x32x16_bf16 v[114:129], v[34:37], v[30:33], v[114:129]
	s_setprio 0
	s_waitcnt lgkmcnt(0)
	s_barrier
	s_setprio 3
	v_exp_f32_e32 v132, v165
	v_exp_f32_e32 v165, v170
	v_exp_f32_e32 v170, v171
	v_exp_f32_e32 v171, v172
	v_mfma_f32_32x32x16_bf16 v[98:113], v[38:41], v[30:33], v[98:113]
	ds_read_b128 v[18:21], v163 offset:18432
	ds_read_b128 v[22:25], v164
	ds_read_b128 v[30:33], v164 offset:32
	ds_read_b128 v[34:37], v163 offset:18464
	v_exp_f32_e32 v172, v173
	v_exp_f32_e32 v173, v174
	v_exp_f32_e32 v174, v175
	v_exp_f32_e32 v175, v188
	v_exp_f32_e32 v188, v189
	v_exp_f32_e32 v133, v200
	s_waitcnt lgkmcnt(2)
	v_mfma_f32_32x32x16_bf16 v[114:129], v[18:21], v[22:25], v[114:129]
	ds_read_b128 v[18:21], v163 offset:23040
	ds_read_b128 v[38:41], v163 offset:23072
	v_exp_f32_e32 v134, v201
	v_exp_f32_e32 v189, v190
	v_exp_f32_e32 v190, v191
	v_exp_f32_e32 v191, v192
	v_exp_f32_e32 v192, v193
	v_exp_f32_e32 v193, v194
	s_waitcnt lgkmcnt(1)
	s_setprio 2
	v_mfma_f32_32x32x16_bf16 v[98:113], v[18:21], v[22:25], v[98:113]
	v_exp_f32_e32 v49, v49
	v_exp_f32_e32 v54, v54
	v_exp_f32_e32 v135, v205
	v_add_f32_e32 v188, 1.0, v188
	v_exp_f32_e32 v55, v55
	v_exp_f32_e32 v56, v56
	v_exp_f32_e32 v57, v57
	v_mfma_f32_32x32x16_bf16 v[114:129], v[34:37], v[30:33], v[114:129]
	v_add_f32_e32 v133, 1.0, v133
	v_add_f32_e32 v134, 1.0, v134
	v_add_f32_e32 v174, 1.0, v174
	v_add_f32_e32 v175, 1.0, v175
	v_add_f32_e32 v194, 1.0, v137
	v_add_f32_e32 v200, 1.0, v139
	v_add_f32_e32 v190, 1.0, v190
	s_waitcnt lgkmcnt(0)
	v_mfma_f32_32x32x16_bf16 v[98:113], v[38:41], v[30:33], v[98:113]
	ds_read_b128 v[14:17], v163 offset:18496
	ds_read_b128 v[18:21], v164 offset:64
	ds_read_b128 v[22:25], v164 offset:96
	ds_read_b128 v[30:33], v163 offset:18528
	v_add_f32_e32 v191, 1.0, v191
	v_add_f32_e32 v192, 1.0, v192
	v_add_f32_e32 v201, 1.0, v140
	v_add_f32_e32 v205, 1.0, v141
	v_add_f32_e32 v132, 1.0, v132
	v_add_f32_e32 v214, 1.0, v50
	s_waitcnt lgkmcnt(2)
	s_setprio 1
	v_mfma_f32_32x32x16_bf16 v[114:129], v[14:17], v[18:21], v[114:129]
	ds_read_b128 v[14:17], v163 offset:23104
	ds_read_b128 v[34:37], v163 offset:23136
	v_add_f32_e32 v215, 1.0, v51
	v_add_f32_e32 v216, 1.0, v52
	v_add_f32_e32 v217, 1.0, v53
	v_add_f32_e32 v193, 1.0, v193
	v_add_f32_e32 v220, 1.0, v46
	v_add_f32_e32 v221, 1.0, v47
	s_waitcnt lgkmcnt(1)
	v_mfma_f32_32x32x16_bf16 v[98:113], v[14:17], v[18:21], v[98:113]
	global_load_dwordx4 v[14:17], v[158:159], off offset:1024
	global_load_dwordx4 v[18:21], v[158:159], off offset:1088
	global_load_dwordx4 v[38:41], v[160:161], off offset:1024
	global_load_dwordx4 v[42:45], v[160:161], off offset:1088
	s_waitcnt vmcnt(7)
	ds_write_b128 v162, v[2:5] offset:36864
	s_waitcnt vmcnt(6)
	ds_write_b128 v162, v[6:9] offset:36928
	s_waitcnt vmcnt(5)
	ds_write_b128 v162, v[10:13] offset:55296
	s_waitcnt vmcnt(4)
	ds_write_b128 v162, v[26:29] offset:55360
	v_mfma_f32_32x32x16_bf16 v[114:129], v[30:33], v[22:25], v[114:129]
	s_setprio 0
	s_waitcnt lgkmcnt(0)
	s_barrier
; __device__ __forceinline__ float sigm_f(float v) { return fast_rcp(1.f + fast_exp2(-v * LOG2E)); }
; __device__ __forceinline__ void p4_pass(const bf16_t* __restrict__ A, int K, const bf16_t* __restrict__ B, int rt, int ct, f32x16& c0, f32x16& c1, LAS char* lds, int tid, int r32, int hi, int wa, int wb) {
;     ...
;     for (int kt = 0; kt < nk; kt += 2) {
;         P4_STEP(kt, ga0, ha0, gb0, hb0, ga1, ha1, gb1, hb1);
;         P4_STEP(kt + 1, ga1, ha1, gb1, hb1, ga0, ha0, gb0, hb0);
;     }
; __device__ __forceinline__ void p4_unit(int rt, int ct, const bf16_t* H, const bf16_t* YA, const bf16_t* YM, const bf16_t* Wga, const bf16_t* Wgm, const bf16_t* Wa, const bf16_t* Wb, bf16_t* MERGED, LAS char* lds) {
;     ...
;     for (int r = 0; r < 16; ++r) { g0[r] = sigm_f(g0[r]); g1[r] = sigm_f(g1[r]); m0[r] = sigm_f(m0[r]); m1[r] = sigm_f(m1[r]); }
	s_setprio 3
	v_add_f32_e32 v222, 1.0, v48
	v_add_f32_e32 v223, 1.0, v49
	v_add_f32_e32 v224, 1.0, v54
	v_rcp_f32_e32 v48, v133
	v_mfma_f32_32x32x16_bf16 v[98:113], v[34:37], v[22:25], v[98:113]
	ds_read_b128 v[2:5], v163 offset:55296
	ds_read_b128 v[6:9], v164 offset:36864
	ds_read_b128 v[10:13], v164 offset:36896
	ds_read_b128 v[22:25], v163 offset:55328
	v_rcp_f32_e32 v49, v134
	v_rcp_f32_e32 v62, v174
	v_rcp_f32_e32 v63, v175
	v_rcp_f32_e32 v64, v145
	v_rcp_f32_e32 v65, v146
	v_rcp_f32_e32 v138, v194
	s_waitcnt lgkmcnt(2)
	v_mfma_f32_32x32x16_bf16 v[114:129], v[2:5], v[6:9], v[114:129]
	ds_read_b128 v[2:5], v163 offset:59904
	ds_read_b128 v[26:29], v163 offset:59936
	v_rcp_f32_e32 v139, v195
	v_rcp_f32_e32 v140, v200
	v_rcp_f32_e32 v141, v190
	v_rcp_f32_e32 v142, v191
	v_rcp_f32_e32 v143, v192
	v_add_f32_e32 v135, 1.0, v135
	s_waitcnt lgkmcnt(1)
	s_setprio 2
	v_mfma_f32_32x32x16_bf16 v[98:113], v[2:5], v[6:9], v[98:113]
	v_add_f32_e32 v165, 1.0, v165
	v_rcp_f32_e32 v46, v0
	v_rcp_f32_e32 v47, v132
	v_add_f32_e32 v170, 1.0, v170
	v_add_f32_e32 v171, 1.0, v171
	v_add_f32_e32 v172, 1.0, v172
	v_add_f32_e32 v173, 1.0, v173
	v_mfma_f32_32x32x16_bf16 v[114:129], v[22:25], v[10:13], v[114:129]
	v_rcp_f32_e32 v50, v135
	v_rcp_f32_e32 v51, v156
	v_rcp_f32_e32 v52, v157
	v_rcp_f32_e32 v53, v165
	v_add_f32_e32 v169, 1.0, v169
	v_add_f32_e32 v189, 1.0, v189
	v_add_f32_e32 v225, 1.0, v55
	s_waitcnt lgkmcnt(0)
	v_mfma_f32_32x32x16_bf16 v[98:113], v[26:29], v[10:13], v[98:113]
	ds_read_b128 v[2:5], v163 offset:55360
	ds_read_b128 v[6:9], v164 offset:36928
	ds_read_b128 v[10:13], v164 offset:36960
	ds_read_b128 v[22:25], v163 offset:55392
	v_add_f32_e32 v226, 1.0, v56
	v_add_f32_e32 v227, 1.0, v57
	v_rcp_f32_e32 v54, v170
	v_rcp_f32_e32 v55, v171
	v_rcp_f32_e32 v56, v172
	v_rcp_f32_e32 v57, v173
	s_waitcnt lgkmcnt(2)
	s_setprio 1
	v_mfma_f32_32x32x16_bf16 v[114:129], v[2:5], v[6:9], v[114:129]
	ds_read_b128 v[2:5], v163 offset:59968
	ds_read_b128 v[26:29], v163 offset:60000
	v_add_f32_e32 v152, 1.0, v152
	v_add_f32_e32 v153, 1.0, v153
	v_add_f32_e32 v154, 1.0, v154
	v_add_f32_e32 v155, 1.0, v155
	v_add_f32_e32 v136, 1.0, v136
	v_add_f32_e32 v210, 1.0, v61
	s_waitcnt lgkmcnt(1)
	v_mfma_f32_32x32x16_bf16 v[98:113], v[2:5], v[6:9], v[98:113]
	global_load_dwordx4 v[2:5], v[158:159], off offset:1152
	v_rcp_f32_e32 v132, v147
	v_rcp_f32_e32 v133, v168
	v_rcp_f32_e32 v134, v169
	v_rcp_f32_e32 v135, v189
	v_rcp_f32_e32 v58, v152
	v_rcp_f32_e32 v59, v153
	v_mfma_f32_32x32x16_bf16 v[114:129], v[22:25], v[10:13], v[114:129]
	s_setprio 0
	global_load_dwordx4 v[6:9], v[158:159], off offset:1216
	global_load_dwordx4 v[22:25], v[160:161], off offset:1152
	global_load_dwordx4 v[30:33], v[160:161], off offset:1216
	s_waitcnt vmcnt(7)
	ds_write_b128 v162, v[14:17]
	s_waitcnt vmcnt(6)
	ds_write_b128 v162, v[18:21] offset:64
	s_waitcnt vmcnt(5)
	ds_write_b128 v162, v[38:41] offset:18432
	s_waitcnt vmcnt(4)
	ds_write_b128 v162, v[42:45] offset:18496
	s_waitcnt lgkmcnt(0)
	s_barrier
	s_setprio 3
	v_rcp_f32_e32 v60, v154
	v_rcp_f32_e32 v61, v155
	v_mfma_f32_32x32x16_bf16 v[98:113], v[26:29], v[10:13], v[98:113]
	ds_read_b128 v[10:13], v163 offset:18432
	ds_read_b128 v[14:17], v164
	ds_read_b128 v[18:21], v164 offset:32
	ds_read_b128 v[26:29], v163 offset:18464
	v_rcp_f32_e32 v137, v136
	v_rcp_f32_e32 v136, v212
	s_waitcnt lgkmcnt(2)
	v_mfma_f32_32x32x16_bf16 v[114:129], v[10:13], v[14:17], v[114:129]
	ds_read_b128 v[10:13], v163 offset:23040
	ds_read_b128 v[34:37], v163 offset:23072
	s_waitcnt lgkmcnt(1)
	s_setprio 2
	v_mfma_f32_32x32x16_bf16 v[98:113], v[10:13], v[14:17], v[98:113]
	v_mfma_f32_32x32x16_bf16 v[114:129], v[26:29], v[18:21], v[114:129]
	s_waitcnt lgkmcnt(0)
	v_mfma_f32_32x32x16_bf16 v[98:113], v[34:37], v[18:21], v[98:113]
	ds_read_b128 v[10:13], v163 offset:18496
	ds_read_b128 v[14:17], v164 offset:64
	ds_read_b128 v[18:21], v164 offset:96
	ds_read_b128 v[26:29], v163 offset:18528
	s_waitcnt lgkmcnt(2)
	s_setprio 1
	v_mfma_f32_32x32x16_bf16 v[114:129], v[10:13], v[14:17], v[114:129]
	ds_read_b128 v[10:13], v163 offset:23104
	ds_read_b128 v[34:37], v163 offset:23136
	s_waitcnt lgkmcnt(1)
	v_mfma_f32_32x32x16_bf16 v[98:113], v[10:13], v[14:17], v[98:113]
	global_load_dwordx4 v[10:13], v[158:159], off offset:1280
	global_load_dwordx4 v[14:17], v[158:159], off offset:1344
	global_load_dwordx4 v[38:41], v[160:161], off offset:1280
	global_load_dwordx4 v[42:45], v[160:161], off offset:1344
	s_waitcnt vmcnt(7)
	ds_write_b128 v162, v[2:5] offset:36864
	s_waitcnt vmcnt(6)
	ds_write_b128 v162, v[6:9] offset:36928
	s_waitcnt vmcnt(5)
	ds_write_b128 v162, v[22:25] offset:55296
	s_waitcnt vmcnt(4)
	ds_write_b128 v162, v[30:33] offset:55360
	v_mfma_f32_32x32x16_bf16 v[114:129], v[26:29], v[18:21], v[114:129]
	s_setprio 0
	s_waitcnt lgkmcnt(0)
	s_barrier
; __device__ __forceinline__ void p4_pass(const bf16_t* __restrict__ A, int K, const bf16_t* __restrict__ B, int rt, int ct, f32x16& c0, f32x16& c1, LAS char* lds, int tid, int r32, int hi, int wa, int wb) {
;     ...
;     for (int kt = 0; kt < nk; kt += 2) {
;         P4_STEP(kt, ga0, ha0, gb0, hb0, ga1, ha1, gb1, hb1);
;         P4_STEP(kt + 1, ga1, ha1, gb1, hb1, ga0, ha0, gb0, hb0);
;     }
	s_setprio 3
	v_mfma_f32_32x32x16_bf16 v[98:113], v[34:37], v[18:21], v[98:113]
	ds_read_b128 v[2:5], v163 offset:55296
	ds_read_b128 v[6:9], v164 offset:36864
	ds_read_b128 v[18:21], v164 offset:36896
	ds_read_b128 v[22:25], v163 offset:55328
	s_waitcnt lgkmcnt(2)
	v_mfma_f32_32x32x16_bf16 v[114:129], v[2:5], v[6:9], v[114:129]
	ds_read_b128 v[2:5], v163 offset:59904
	ds_read_b128 v[26:29], v163 offset:59936
	s_waitcnt lgkmcnt(1)
	s_setprio 2
	v_mfma_f32_32x32x16_bf16 v[98:113], v[2:5], v[6:9], v[98:113]
	v_mfma_f32_32x32x16_bf16 v[114:129], v[22:25], v[18:21], v[114:129]
	s_waitcnt lgkmcnt(0)
	v_mfma_f32_32x32x16_bf16 v[98:113], v[26:29], v[18:21], v[98:113]
	ds_read_b128 v[2:5], v163 offset:55360
	ds_read_b128 v[6:9], v164 offset:36928
	ds_read_b128 v[18:21], v164 offset:36960
	ds_read_b128 v[22:25], v163 offset:55392
	s_waitcnt lgkmcnt(2)
	s_setprio 1
	v_mfma_f32_32x32x16_bf16 v[114:129], v[2:5], v[6:9], v[114:129]
	ds_read_b128 v[2:5], v163 offset:59968
	ds_read_b128 v[26:29], v163 offset:60000
	s_waitcnt lgkmcnt(1)
	v_mfma_f32_32x32x16_bf16 v[98:113], v[2:5], v[6:9], v[98:113]
	global_load_dwordx4 v[2:5], v[158:159], off offset:1408
	v_mfma_f32_32x32x16_bf16 v[114:129], v[22:25], v[18:21], v[114:129]
	s_setprio 0
	global_load_dwordx4 v[6:9], v[158:159], off offset:1472
	global_load_dwordx4 v[22:25], v[160:161], off offset:1408
	global_load_dwordx4 v[30:33], v[160:161], off offset:1472
	s_waitcnt vmcnt(7)
	ds_write_b128 v162, v[10:13]
	s_waitcnt vmcnt(6)
	ds_write_b128 v162, v[14:17] offset:64
	s_waitcnt vmcnt(5)
	ds_write_b128 v162, v[38:41] offset:18432
	s_waitcnt vmcnt(4)
	ds_write_b128 v162, v[42:45] offset:18496
	s_waitcnt lgkmcnt(0)
	s_barrier
	s_setprio 3
	v_mfma_f32_32x32x16_bf16 v[98:113], v[26:29], v[18:21], v[98:113]
	ds_read_b128 v[10:13], v163 offset:18432
	ds_read_b128 v[14:17], v164
	ds_read_b128 v[18:21], v164 offset:32
	ds_read_b128 v[26:29], v163 offset:18464
	s_waitcnt lgkmcnt(2)
	v_mfma_f32_32x32x16_bf16 v[114:129], v[10:13], v[14:17], v[114:129]
	ds_read_b128 v[10:13], v163 offset:23040
	ds_read_b128 v[34:37], v163 offset:23072
	s_waitcnt lgkmcnt(1)
	s_setprio 2
	v_mfma_f32_32x32x16_bf16 v[98:113], v[10:13], v[14:17], v[98:113]
	v_mfma_f32_32x32x16_bf16 v[114:129], v[26:29], v[18:21], v[114:129]
	s_waitcnt lgkmcnt(0)
	v_mfma_f32_32x32x16_bf16 v[98:113], v[34:37], v[18:21], v[98:113]
	ds_read_b128 v[10:13], v163 offset:18496
	ds_read_b128 v[14:17], v164 offset:64
	ds_read_b128 v[18:21], v164 offset:96
	ds_read_b128 v[26:29], v163 offset:18528
	s_waitcnt lgkmcnt(2)
	s_setprio 1
	v_mfma_f32_32x32x16_bf16 v[114:129], v[10:13], v[14:17], v[114:129]
	ds_read_b128 v[10:13], v163 offset:23104
	ds_read_b128 v[34:37], v163 offset:23136
	s_waitcnt lgkmcnt(1)
	v_mfma_f32_32x32x16_bf16 v[98:113], v[10:13], v[14:17], v[98:113]
	global_load_dwordx4 v[10:13], v[158:159], off offset:1536
	global_load_dwordx4 v[14:17], v[158:159], off offset:1600
	global_load_dwordx4 v[38:41], v[160:161], off offset:1536
	global_load_dwordx4 v[42:45], v[160:161], off offset:1600
	s_waitcnt vmcnt(7)
	ds_write_b128 v162, v[2:5] offset:36864
	s_waitcnt vmcnt(6)
	ds_write_b128 v162, v[6:9] offset:36928
	s_waitcnt vmcnt(5)
	ds_write_b128 v162, v[22:25] offset:55296
	s_waitcnt vmcnt(4)
	ds_write_b128 v162, v[30:33] offset:55360
	v_mfma_f32_32x32x16_bf16 v[114:129], v[26:29], v[18:21], v[114:129]
	s_setprio 0
	s_waitcnt lgkmcnt(0)
	s_barrier
	s_setprio 3
	v_mfma_f32_32x32x16_bf16 v[98:113], v[34:37], v[18:21], v[98:113]
	ds_read_b128 v[2:5], v163 offset:55296
	ds_read_b128 v[6:9], v164 offset:36864
	ds_read_b128 v[18:21], v164 offset:36896
	ds_read_b128 v[22:25], v163 offset:55328
	s_waitcnt lgkmcnt(2)
	v_mfma_f32_32x32x16_bf16 v[114:129], v[2:5], v[6:9], v[114:129]
	ds_read_b128 v[2:5], v163 offset:59904
	ds_read_b128 v[26:29], v163 offset:59936
	s_waitcnt lgkmcnt(1)
	s_setprio 2
	v_mfma_f32_32x32x16_bf16 v[98:113], v[2:5], v[6:9], v[98:113]
	v_mfma_f32_32x32x16_bf16 v[114:129], v[22:25], v[18:21], v[114:129]
	s_waitcnt lgkmcnt(0)
	v_mfma_f32_32x32x16_bf16 v[98:113], v[26:29], v[18:21], v[98:113]
	ds_read_b128 v[2:5], v163 offset:55360
	ds_read_b128 v[6:9], v164 offset:36928
	ds_read_b128 v[18:21], v164 offset:36960
	ds_read_b128 v[22:25], v163 offset:55392
	s_waitcnt lgkmcnt(2)
	s_setprio 1
	v_mfma_f32_32x32x16_bf16 v[114:129], v[2:5], v[6:9], v[114:129]
	ds_read_b128 v[2:5], v163 offset:59968
	ds_read_b128 v[26:29], v163 offset:60000
	s_waitcnt lgkmcnt(1)
	v_mfma_f32_32x32x16_bf16 v[98:113], v[2:5], v[6:9], v[98:113]
	global_load_dwordx4 v[2:5], v[158:159], off offset:1664
	v_mfma_f32_32x32x16_bf16 v[114:129], v[22:25], v[18:21], v[114:129]
	s_setprio 0
	global_load_dwordx4 v[6:9], v[158:159], off offset:1728
	global_load_dwordx4 v[22:25], v[160:161], off offset:1664
	global_load_dwordx4 v[30:33], v[160:161], off offset:1728
	s_waitcnt vmcnt(7)
	ds_write_b128 v162, v[10:13]
	s_waitcnt vmcnt(6)
	ds_write_b128 v162, v[14:17] offset:64
	s_waitcnt vmcnt(5)
	ds_write_b128 v162, v[38:41] offset:18432
	s_waitcnt vmcnt(4)
	ds_write_b128 v162, v[42:45] offset:18496
	s_waitcnt lgkmcnt(0)
	s_barrier
; __device__ __forceinline__ float sigm_f(float v) { return fast_rcp(1.f + fast_exp2(-v * LOG2E)); }
; __device__ __forceinline__ void p4_pass(const bf16_t* __restrict__ A, int K, const bf16_t* __restrict__ B, int rt, int ct, f32x16& c0, f32x16& c1, LAS char* lds, int tid, int r32, int hi, int wa, int wb) {
;     ...
;     for (int kt = 0; kt < nk; kt += 2) {
;         P4_STEP(kt, ga0, ha0, gb0, hb0, ga1, ha1, gb1, hb1);
;         P4_STEP(kt + 1, ga1, ha1, gb1, hb1, ga0, ha0, gb0, hb0);
;     }
; __device__ __forceinline__ void p4_unit(int rt, int ct, const bf16_t* H, const bf16_t* YA, const bf16_t* YM, const bf16_t* Wga, const bf16_t* Wgm, const bf16_t* Wa, const bf16_t* Wb, bf16_t* MERGED, LAS char* lds) {
;     ...
;     for (int r = 0; r < 16; ++r) { g0[r] = sigm_f(g0[r]); g1[r] = sigm_f(g1[r]); m0[r] = sigm_f(m0[r]); m1[r] = sigm_f(m1[r]); }
	s_setprio 3
	v_mfma_f32_32x32x16_bf16 v[98:113], v[26:29], v[18:21], v[98:113]
	ds_read_b128 v[10:13], v163 offset:18432
	ds_read_b128 v[14:17], v164
	ds_read_b128 v[18:21], v164 offset:32
	ds_read_b128 v[26:29], v163 offset:18464
	s_waitcnt lgkmcnt(2)
	v_mfma_f32_32x32x16_bf16 v[114:129], v[10:13], v[14:17], v[114:129]
	ds_read_b128 v[10:13], v163 offset:23040
	ds_read_b128 v[34:37], v163 offset:23072
	s_waitcnt lgkmcnt(1)
	s_setprio 2
	v_mfma_f32_32x32x16_bf16 v[98:113], v[10:13], v[14:17], v[98:113]
	v_mfma_f32_32x32x16_bf16 v[114:129], v[26:29], v[18:21], v[114:129]
	s_waitcnt lgkmcnt(0)
	v_mfma_f32_32x32x16_bf16 v[98:113], v[34:37], v[18:21], v[98:113]
	ds_read_b128 v[10:13], v163 offset:18496
	ds_read_b128 v[14:17], v164 offset:64
	ds_read_b128 v[18:21], v164 offset:96
	ds_read_b128 v[26:29], v163 offset:18528
	s_waitcnt lgkmcnt(2)
	s_setprio 1
	v_mfma_f32_32x32x16_bf16 v[114:129], v[10:13], v[14:17], v[114:129]
	ds_read_b128 v[10:13], v163 offset:23104
	ds_read_b128 v[34:37], v163 offset:23136
	s_waitcnt lgkmcnt(1)
	v_mfma_f32_32x32x16_bf16 v[98:113], v[10:13], v[14:17], v[98:113]
	global_load_dwordx4 v[10:13], v[158:159], off offset:1792
	global_load_dwordx4 v[14:17], v[158:159], off offset:1856
	global_load_dwordx4 v[38:41], v[160:161], off offset:1792
	global_load_dwordx4 v[42:45], v[160:161], off offset:1856
	s_waitcnt vmcnt(7)
	ds_write_b128 v162, v[2:5] offset:36864
	s_waitcnt vmcnt(6)
	ds_write_b128 v162, v[6:9] offset:36928
	s_waitcnt vmcnt(5)
	ds_write_b128 v162, v[22:25] offset:55296
	s_waitcnt vmcnt(4)
	ds_write_b128 v162, v[30:33] offset:55360
	v_mfma_f32_32x32x16_bf16 v[114:129], v[26:29], v[18:21], v[114:129]
	s_setprio 0
	s_waitcnt lgkmcnt(0)
	s_barrier
	s_setprio 3
	v_mfma_f32_32x32x16_bf16 v[98:113], v[34:37], v[18:21], v[98:113]
	ds_read_b128 v[2:5], v163 offset:55296
	ds_read_b128 v[6:9], v164 offset:36864
	ds_read_b128 v[18:21], v164 offset:36896
	ds_read_b128 v[22:25], v163 offset:55328
	s_waitcnt lgkmcnt(2)
	v_mfma_f32_32x32x16_bf16 v[114:129], v[2:5], v[6:9], v[114:129]
	ds_read_b128 v[2:5], v163 offset:59904
	ds_read_b128 v[26:29], v163 offset:59936
	s_waitcnt lgkmcnt(1)
	s_setprio 2
	v_mfma_f32_32x32x16_bf16 v[98:113], v[2:5], v[6:9], v[98:113]
	v_mfma_f32_32x32x16_bf16 v[114:129], v[22:25], v[18:21], v[114:129]
	s_waitcnt lgkmcnt(0)
	v_mfma_f32_32x32x16_bf16 v[98:113], v[26:29], v[18:21], v[98:113]
	ds_read_b128 v[2:5], v163 offset:55360
	ds_read_b128 v[6:9], v164 offset:36928
	ds_read_b128 v[18:21], v164 offset:36960
	ds_read_b128 v[22:25], v163 offset:55392
	s_waitcnt lgkmcnt(2)
	s_setprio 1
	v_mfma_f32_32x32x16_bf16 v[114:129], v[2:5], v[6:9], v[114:129]
	ds_read_b128 v[2:5], v163 offset:59968
	ds_read_b128 v[26:29], v163 offset:60000
	s_waitcnt lgkmcnt(1)
	v_mfma_f32_32x32x16_bf16 v[98:113], v[2:5], v[6:9], v[98:113]
	global_load_dwordx4 v[2:5], v[158:159], off offset:1920
	v_mfma_f32_32x32x16_bf16 v[114:129], v[22:25], v[18:21], v[114:129]
	s_setprio 0
	global_load_dwordx4 v[6:9], v[158:159], off offset:1984
	global_load_dwordx4 v[22:25], v[160:161], off offset:1920
	global_load_dwordx4 v[30:33], v[160:161], off offset:1984
	s_waitcnt vmcnt(7)
	ds_write_b128 v162, v[10:13]
	s_waitcnt vmcnt(6)
	ds_write_b128 v162, v[14:17] offset:64
	s_waitcnt vmcnt(5)
	ds_write_b128 v162, v[38:41] offset:18432
	s_waitcnt vmcnt(4)
	ds_write_b128 v162, v[42:45] offset:18496
	s_waitcnt lgkmcnt(0)
	s_barrier
	s_setprio 3
	v_rcp_f32_e32 v38, v188
	v_rcp_f32_e32 v39, v148
	v_mfma_f32_32x32x16_bf16 v[98:113], v[26:29], v[18:21], v[98:113]
	ds_read_b128 v[10:13], v163 offset:18432
	ds_read_b128 v[14:17], v164
	ds_read_b128 v[18:21], v164 offset:32
	ds_read_b128 v[26:29], v163 offset:18464
	v_rcp_f32_e32 v40, v149
	v_rcp_f32_e32 v41, v150
	v_rcp_f32_e32 v42, v151
	v_rcp_f32_e32 v43, v166
	v_rcp_f32_e32 v44, v167
	v_rcp_f32_e32 v45, v144
	s_waitcnt lgkmcnt(2)
	v_mfma_f32_32x32x16_bf16 v[114:129], v[10:13], v[14:17], v[114:129]
	ds_read_b128 v[10:13], v163 offset:23040
	ds_read_b128 v[34:37], v163 offset:23072
	s_waitcnt lgkmcnt(1)
	s_setprio 2
	v_mfma_f32_32x32x16_bf16 v[98:113], v[10:13], v[14:17], v[98:113]
	v_mfma_f32_32x32x16_bf16 v[114:129], v[26:29], v[18:21], v[114:129]
	s_waitcnt lgkmcnt(0)
	s_setprio 1
	v_mfma_f32_32x32x16_bf16 v[98:113], v[34:37], v[18:21], v[98:113]
	ds_read_b128 v[10:13], v163 offset:18496
	ds_read_b128 v[14:17], v164 offset:64
	ds_read_b128 v[18:21], v164 offset:96
	ds_read_b128 v[26:29], v163 offset:18528
	s_waitcnt lgkmcnt(2)
	v_mfma_f32_32x32x16_bf16 v[114:129], v[10:13], v[14:17], v[114:129]
	ds_read_b128 v[10:13], v163 offset:23104
	ds_read_b128 v[34:37], v163 offset:23136
	s_waitcnt vmcnt(3)
	ds_write_b128 v162, v[2:5] offset:36864
	s_waitcnt vmcnt(2)
	ds_write_b128 v162, v[6:9] offset:36928
	s_waitcnt vmcnt(1)
	ds_write_b128 v162, v[22:25] offset:55296
	s_waitcnt vmcnt(0)
	ds_write_b128 v162, v[30:33] offset:55360
	s_waitcnt lgkmcnt(5)
	v_mfma_f32_32x32x16_bf16 v[98:113], v[10:13], v[14:17], v[98:113]
	s_setprio 0
	s_waitcnt lgkmcnt(0)
	s_barrier
; __device__ __forceinline__ unsigned cvt_pk_bf16(float lo, float hi) { unsigned r; asm volatile("v_cvt_pk_bf16_f32 %0, %1, %2" : "=v"(r) : "v"(lo), "v"(hi)); return r; }
; __device__ __forceinline__ float sigm_f(float v) { return fast_rcp(1.f + fast_exp2(-v * LOG2E)); }
; __device__ __forceinline__ void p4_pass(const bf16_t* __restrict__ A, int K, const bf16_t* __restrict__ B, int rt, int ct, f32x16& c0, f32x16& c1, LAS char* lds, int tid, int r32, int hi, int wa, int wb) {
;     ...
;     for (int kt = 0; kt < nk; kt += 2) {
;         P4_STEP(kt, ga0, ha0, gb0, hb0, ga1, ha1, gb1, hb1);
;         P4_STEP(kt + 1, ga1, ha1, gb1, hb1, ga0, ha0, gb0, hb0);
;     }
; __device__ __forceinline__ void p4_unit(int rt, int ct, const bf16_t* H, const bf16_t* YA, const bf16_t* YM, const bf16_t* Wga, const bf16_t* Wgm, const bf16_t* Wa, const bf16_t* Wb, bf16_t* MERGED, LAS char* lds) {
;     ...
;     for (int r = 0; r < 16; ++r) { g0[r] = sigm_f(g0[r]); g1[r] = sigm_f(g1[r]); m0[r] = sigm_f(m0[r]); m1[r] = sigm_f(m1[r]); }
;     p4_pass(YA, 512, Wa, rt, ct, c0, c1, lds, tid, r32, hi, wa, wb);
;     g0 *= c0; g1 *= c1;
;     p4_pass(YM, 1024, Wb, rt, ct, c0, c1, lds, tid, r32, hi, wa, wb);
;     g0 += m0 * c0; g1 += m1 * c1;
;     bf16_t* op = MERGED + (size_t)(rt * 128 + wa * 32 + r32) * 1024 + ct * 128 + wb * 64 + 4 * hi;
; #pragma unroll
;     for (int g4 = 0; g4 < 4; ++g4) { u32x2 w; w.x = cvt_pk_bf16(g0[4 * g4], g0[4 * g4 + 1]); w.y = cvt_pk_bf16(g0[4 * g4 + 2], g0[4 * g4 + 3]); *(u32x2*)(op + 8 * g4) = w;
;         u32x2 v; v.x = cvt_pk_bf16(g1[4 * g4], g1[4 * g4 + 1]); v.y = cvt_pk_bf16(g1[4 * g4 + 2], g1[4 * g4 + 3]); *(u32x2*)(op + 32 + 8 * g4) = v; }
	s_setprio 3
	ds_read_b128 v[2:5], v163 offset:55296
	ds_read_b128 v[6:9], v164 offset:36864
	ds_read_b128 v[10:13], v164 offset:36896
	ds_read_b128 v[14:17], v163 offset:55328
	v_rcp_f32_e32 v22, v201
	v_rcp_f32_e32 v23, v205
	v_rcp_f32_e32 v24, v206
	v_mfma_f32_32x32x16_bf16 v[114:129], v[26:29], v[18:21], v[114:129]
	v_rcp_f32_e32 v25, v207
	v_rcp_f32_e32 v26, v208
	v_rcp_f32_e32 v27, v209
	v_rcp_f32_e32 v32, v214
	v_rcp_f32_e32 v33, v215
	v_rcp_f32_e32 v28, v210
	v_rcp_f32_e32 v29, v211
	v_mfma_f32_32x32x16_bf16 v[98:113], v[34:37], v[18:21], v[98:113]
	v_rcp_f32_e32 v34, v216
	v_rcp_f32_e32 v35, v217
	v_rcp_f32_e32 v31, v213
	v_rcp_f32_e32 v30, v227
	s_waitcnt lgkmcnt(2)
	s_setprio 2
	v_mfma_f32_32x32x16_bf16 v[114:129], v[2:5], v[6:9], v[114:129]
	ds_read_b128 v[2:5], v163 offset:59904
	ds_read_b128 v[18:21], v163 offset:59936
	s_waitcnt lgkmcnt(1)
	v_mfma_f32_32x32x16_bf16 v[98:113], v[2:5], v[6:9], v[98:113]
	s_setprio 1
	v_mfma_f32_32x32x16_bf16 v[114:129], v[14:17], v[10:13], v[114:129]
	s_waitcnt lgkmcnt(0)
	v_mfma_f32_32x32x16_bf16 v[98:113], v[18:21], v[10:13], v[98:113]
	ds_read_b128 v[2:5], v163 offset:55360
	ds_read_b128 v[6:9], v164 offset:36928
	ds_read_b128 v[10:13], v164 offset:36960
	ds_read_b128 v[14:17], v163 offset:55392
	s_waitcnt lgkmcnt(2)
	v_mfma_f32_32x32x16_bf16 v[114:129], v[2:5], v[6:9], v[114:129]
	s_setprio 0
	ds_read_b128 v[2:5], v163 offset:59968
	ds_read_b128 v[18:21], v163 offset:60000
	s_waitcnt lgkmcnt(0)
	s_barrier
	v_mfma_f32_32x32x16_bf16 v[98:113], v[2:5], v[6:9], v[98:113]
	v_rcp_f32_e32 v2, v218
	v_rcp_f32_e32 v3, v219
	v_rcp_f32_e32 v4, v193
	v_rcp_f32_e32 v5, v220
	v_rcp_f32_e32 v6, v221
	v_rcp_f32_e32 v7, v222
	v_rcp_f32_e32 v8, v223
	v_mfma_f32_32x32x16_bf16 v[114:129], v[14:17], v[10:13], v[114:129]
	v_rcp_f32_e32 v9, v224
	v_rcp_f32_e32 v14, v225
	v_rcp_f32_e32 v15, v226
	v_mfma_f32_32x32x16_bf16 v[98:113], v[18:21], v[10:13], v[98:113]
	s_nop 7
	v_mul_f32_e64 v10, v38, v116
	v_mul_f32_e64 v11, v39, v117
	v_mul_f32_e64 v12, v40, v118
	v_mul_f32_e64 v13, v41, v119
	v_mul_f32_e64 v16, v42, v120
	v_mul_f32_e64 v17, v43, v121
	v_pk_mul_f32 v[18:19], v[44:45], v[122:123]
	v_pk_mul_f32 v[20:21], v[64:65], v[124:125]
	v_pk_mul_f32 v[40:41], v[62:63], v[114:115]
	v_pk_fma_f32 v[10:11], v[48:49], v[84:85], v[10:11]
	v_pk_mul_f32 v[42:43], v[140:141], v[100:101]
	v_pk_mul_f32 v[44:45], v[142:143], v[102:103]
	v_pk_mul_f32 v[22:23], v[22:23], v[104:105]
	v_pk_mul_f32 v[24:25], v[24:25], v[106:107]
	v_pk_mul_f32 v[26:27], v[26:27], v[108:109]
	v_pk_mul_f32 v[64:65], v[138:139], v[98:99]
	v_pk_fma_f32 v[40:41], v[46:47], v[82:83], v[40:41]
	v_pk_fma_f32 v[8:9], v[8:9], v[76:77], v[26:27]
	v_pk_fma_f32 v[6:7], v[6:7], v[74:75], v[24:25]
	v_pk_fma_f32 v[4:5], v[4:5], v[72:73], v[22:23]
	v_pk_fma_f32 v[2:3], v[2:3], v[70:71], v[44:45]
	v_pk_fma_f32 v[22:23], v[34:35], v[68:69], v[42:43]
	v_pk_fma_f32 v[24:25], v[32:33], v[66:67], v[64:65]
	v_cvt_pk_bf16_f32 v26, v40, v41
	v_cvt_pk_bf16_f32 v27, v10, v11
	global_store_dwordx2 v[130:131], v[26:27], off
	v_cvt_pk_bf16_f32 v10, v24, v25
	v_cvt_pk_bf16_f32 v11, v22, v23
	v_pk_fma_f32 v[16:17], v[52:53], v[88:89], v[16:17]
	v_pk_fma_f32 v[12:13], v[50:51], v[86:87], v[12:13]
	global_store_dwordx2 v[130:131], v[10:11], off offset:64
	v_cvt_pk_bf16_f32 v10, v12, v13
	v_cvt_pk_bf16_f32 v11, v16, v17
	global_store_dwordx2 v[130:131], v[10:11], off offset:16
	v_cvt_pk_bf16_f32 v2, v2, v3
	v_cvt_pk_bf16_f32 v3, v4, v5
	v_pk_fma_f32 v[20:21], v[56:57], v[92:93], v[20:21]
	v_pk_fma_f32 v[18:19], v[54:55], v[90:91], v[18:19]
	global_store_dwordx2 v[130:131], v[2:3], off offset:80
	v_cvt_pk_bf16_f32 v2, v18, v19
	v_cvt_pk_bf16_f32 v3, v20, v21
	v_pk_mul_f32 v[36:37], v[132:133], v[126:127]
	v_pk_mul_f32 v[38:39], v[134:135], v[128:129]
	global_store_dwordx2 v[130:131], v[2:3], off offset:32
	v_cvt_pk_bf16_f32 v2, v6, v7
	v_cvt_pk_bf16_f32 v3, v8, v9
	v_pk_mul_f32 v[28:29], v[28:29], v[110:111]
	v_pk_mul_f32 v[62:63], v[136:137], v[112:113]
	v_pk_fma_f32 v[38:39], v[60:61], v[96:97], v[38:39]
	v_pk_fma_f32 v[36:37], v[58:59], v[94:95], v[36:37]
	global_store_dwordx2 v[130:131], v[2:3], off offset:96
	v_cvt_pk_bf16_f32 v2, v36, v37
	v_cvt_pk_bf16_f32 v3, v38, v39
	v_pk_fma_f32 v[30:31], v[30:31], v[80:81], v[62:63]
	v_pk_fma_f32 v[14:15], v[14:15], v[78:79], v[28:29]
	global_store_dwordx2 v[130:131], v[2:3], off offset:48
	v_cvt_pk_bf16_f32 v2, v14, v15
	v_cvt_pk_bf16_f32 v3, v30, v31
	global_store_dwordx2 v[130:131], v[2:3], off offset:112
	s_cbranch_scc1 .LBB0_848
